# one static priority raise for waves 4-7 during each GEMM phase (no per-segment flips)
# speedup vs baseline: 1.0106x; 1.0027x over previous
; #define TID() int lane_v_; asm volatile("v_mbcnt_lo_u32_b32 %0, -1, 0\n\tv_mbcnt_hi_u32_b32 %0, -1, %0" : "=v"(lane_v_)); const int tid = wave_s * 64 + lane_v_
; #define PTRS() kptr_t kp = kargs(); unsigned char* ws = kws(kp); (void)ws
;     __host__ __device__ bool next(int i, Unit& u) const {
;         const long L = (long)i * G + c; if (L >= nwg) return false;
;         int wgid = (int)L; { const int q = nwg / NXCD, r = nwg % NXCD, xcd = wgid % NXCD, off = wgid / NXCD; wgid = (xcd < r ? xcd * (q + 1) : r * (q + 1) + (xcd - r) * q) + off; }
;         const int nig = wgm * nN, gid = wgid / nig, fm = gid * wgm, gsz = (nM - fm) < wgm ? (nM - fm) : wgm;
;         u.pm = fm + ((wgid % nig) % gsz); u.pn = (wgid % nig) / gsz; return true;
; __global__ void __launch_bounds__(NTHR, 2) hybrid_fwd(Args a) {
;     ...
;     if (IN(1)) for (int rep_ = 0; rep_ < REPS(1); ++rep_) { TID(); PTRS();
;         { pg8::Gemm g{S1, (const bf16_t*)(ws + WS_WQKVZ), M, ATT_IN, D}; pg8::StaticOrder S; S.init(M, ATT_IN, G, bid);
;           pg8::EpiQKVZ E{QKVZ, (const float*)(ws + WS_BIAS), (const float*)(ws + WS_COS), (const float*)(ws + WS_SIN)};
;           pg8::gemm_phase<pg8::EpiQKVZ, pg8::StaticOrder, true, true>(lds, g, S, E, tid); }
.LBB0_115:
	v_readlane_b32 s2, v254, 1
	v_readlane_b32 s3, v254, 2
	s_cmp_lt_i32 s2, 2
	s_cselect_b64 s[2:3], -1, 0
	s_and_b64 s[6:7], s[2:3], s[0:1]
	s_andn2_b64 vcc, exec, s[6:7]
	v_writelane_b32 v254, s52, 3
	s_cbranch_vccnz .LBB0_170
	v_readlane_b32 s98, v254, 3
	s_cmp_ge_u32 s98, 0x100
	s_cbranch_scc0 .Lmy_prio_1
	s_setprio 1
.Lmy_prio_1:
	s_cmpk_lt_i32 s84, 0x500
	s_cselect_b64 s[0:1], -1, 0
	s_ashr_i32 s50, s84, 31
	s_lshr_b32 s2, s50, 29
	s_add_i32 s2, s84, s2
	s_ashr_i32 s33, s2, 3
	s_and_b32 s2, s2, -8
	s_sub_i32 s38, s84, s2
	s_mov_b64 s[2:3], s[82:83]
	v_mbcnt_lo_u32_b32 v172, -1, 0
	v_mbcnt_hi_u32_b32 v172, -1, v172
	s_load_dwordx2 s[8:9], s[2:3], 0xc8
	s_cmp_lt_i32 s38, 0
	v_add_u32_e32 v176, s52, v172
	s_waitcnt lgkmcnt(0)
	s_cselect_b64 s[10:11], -1, 0
	s_cmpk_gt_i32 s84, 0x4ff
	v_readfirstlane_b32 s2, v176
	s_cbranch_scc1 .LBB0_118
	s_movk_i32 s3, 0xa1
	s_and_b64 s[4:5], s[10:11], exec
	s_cselect_b32 s3, s3, 0xa0
	s_mul_i32 s3, s38, s3
	s_add_i32 s3, s3, s33
	s_mul_hi_i32 s4, s3, 0x88888889
	s_add_i32 s4, s4, s3
	s_lshr_b32 s5, s4, 31
	s_ashr_i32 s4, s4, 6
	s_add_i32 s4, s4, s5
	s_mul_i32 s12, s4, 12
	s_sub_i32 s5, 0x80, s12
	s_mulk_i32 s4, 0x78
	s_min_u32 s13, s5, 12
	s_sub_i32 s3, s3, s4
	s_sext_i32_i8 s4, s3
	v_cvt_f32_ubyte0_e32 v1, s13
	v_cvt_f32_i32_e32 v0, s4
	v_rcp_iflag_f32_e32 v2, v1
	s_ashr_i32 s4, s4, 30
	s_or_b32 s14, s4, 1
	v_mul_f32_e32 v2, v0, v2
	v_trunc_f32_e32 v2, v2
	v_fma_f32 v0, -v2, v1, v0
	v_cvt_i32_f32_e32 v2, v2
	v_cmp_ge_f32_e64 s[4:5], |v0|, v1
	s_and_b64 s[4:5], s[4:5], exec
	s_cselect_b32 s4, s14, 0
	v_readfirstlane_b32 s5, v2
	s_add_i32 s5, s5, s4
	s_sext_i32_i8 s4, s5
	s_mul_i32 s5, s5, s13
	s_sub_i32 s3, s3, s5
	s_sext_i32_i8 s3, s3
	s_add_i32 s30, s12, s3

; __device__ __forceinline__ unsigned xb_ld(unsigned* p)              { return __hip_atomic_load(p, __ATOMIC_RELAXED, __HIP_MEMORY_SCOPE_AGENT); }
; __device__ __forceinline__ unsigned xb_add(unsigned* p, unsigned v) { return __hip_atomic_fetch_add(p, v, __ATOMIC_RELAXED, __HIP_MEMORY_SCOPE_AGENT); }
; __device__ __forceinline__ void xcd_barrier_complete(unsigned* bar, unsigned x, unsigned& nloc, unsigned& nx) {
;     const unsigned G = gridDim.x * gridDim.y * gridDim.z;
;     unsigned sum, cnt, mine, sp = 0u;
;     for (;;) {
;         sum = 0u; cnt = 0u; mine = 0u;
; #pragma unroll
;         for (unsigned j = 0; j < 16; ++j) { const unsigned c = xb_ld(&bar[XB_XCNT(j)]); sum += c; cnt += (c > 0u) ? 1u : 0u; mine = (j == x) ? c : mine; }
; __device__ __forceinline__ void xcd_barrier(const XcdBarrier& b, const int tid_) {
;     asm volatile("s_waitcnt vmcnt(0)" ::: "memory");
;     __syncthreads();
;     if (tid_ == 0) {
;         unsigned* bar = b.bar;
;         __builtin_amdgcn_s_waitcnt(0);
;         unsigned nloc = b.st[0], nx = b.st[1];
;         if (nloc == 0u) { xcd_barrier_complete(bar, b.x, nloc, nx); b.st[0] = nloc; b.st[1] = nx; }
;         const unsigned old = xb_add(&bar[XB_XSUB(b.x)], 1u);
.LBB0_170:
	s_setprio 0
	v_readlane_b32 s0, v254, 1
	v_readlane_b32 s1, v254, 2
	s_cmp_gt_i32 s1, 2
	s_cselect_b64 s[0:1], -1, 0
	s_and_b64 s[2:3], s[6:7], s[0:1]
	s_andn2_b64 vcc, exec, s[2:3]
	s_cbranch_vccnz .LBB0_224
	s_mov_b64 s[4:5], s[82:83]
	v_mbcnt_lo_u32_b32 v0, -1, 0
	v_mbcnt_hi_u32_b32 v0, -1, v0
	s_getreg_b32 s6, hwreg(HW_REG_XCC_ID, 0, 4)
	s_waitcnt vmcnt(0)
	v_sub_u32_e32 v0, 0, v0
	v_cmp_eq_u32_e32 vcc, s52, v0
	s_waitcnt vmcnt(0) lgkmcnt(0)
	s_barrier
	s_and_saveexec_b64 s[2:3], vcc
	s_cbranch_execz .LBB0_223
	s_add_i32 s7, 0, 0x23fc0
	v_mov_b32_e32 v0, s7
	s_load_dwordx2 s[4:5], s[4:5], 0xc8
	s_waitcnt vmcnt(0) expcnt(0) lgkmcnt(0)
	ds_read_b32 v2, v0
	s_add_i32 s7, 0, 0x23fc4
	v_mov_b32_e32 v0, s7
	ds_read_b32 v0, v0
	s_and_b32 s33, s6, 15
	s_waitcnt lgkmcnt(1)
	v_cmp_ne_u32_e32 vcc, 0, v2
	s_cbranch_vccnz .LBB0_187
	s_load_dword s6, s[82:83], 0xe0
	s_mov_b32 s49, 1
	v_mov_b32_e32 v16, 0
	s_waitcnt lgkmcnt(0)
	s_mul_i32 s48, s55, s6
	s_add_u32 s6, s4, 0x1900200
	s_addc_u32 s7, s5, 0
	s_add_u32 s8, s4, 0x1900400
	s_addc_u32 s9, s5, 0
	s_add_u32 s10, s4, 0x1900500
	s_addc_u32 s11, s5, 0
	s_add_u32 s12, s4, 0x1900600
	s_addc_u32 s13, s5, 0
	s_add_u32 s14, s4, 0x1900700
	s_addc_u32 s15, s5, 0
	s_add_u32 s16, s4, 0x1900800
	s_addc_u32 s17, s5, 0
	s_add_u32 s18, s4, 0x1900900
	s_addc_u32 s19, s5, 0
	s_add_u32 s20, s4, 0x1900a00
	s_addc_u32 s21, s5, 0
	s_add_u32 s22, s4, 0x1900b00
	s_addc_u32 s23, s5, 0
	s_add_u32 s24, s4, 0x1900c00
	s_addc_u32 s25, s5, 0
	s_add_u32 s26, s4, 0x1900d00
	s_addc_u32 s27, s5, 0
	s_add_u32 s28, s4, 0x1900e00
	s_addc_u32 s29, s5, 0
	s_add_u32 s30, s4, 0x1900f00
	s_addc_u32 s31, s5, 0
	s_add_u32 s34, s4, 0x1901000
	s_addc_u32 s35, s5, 0
	s_add_u32 s36, s4, 0x1901100
	s_addc_u32 s37, s5, 0
	s_add_u32 s38, s4, 0x1901200
	s_addc_u32 s39, s5, 0
	s_add_u32 s40, s4, 0x1901300
	s_mul_i32 s48, s48, s54
	s_addc_u32 s41, s5, 0
	s_branch .LBB0_175

; #define PG8_BAR __builtin_amdgcn_s_barrier()
;     __host__ __device__ bool next(int i, Unit& u) const {
;         const long L = (long)i * G + c; if (L >= nwg) return false;
;         int wgid = (int)L; { const int q = nwg / NXCD, r = nwg % NXCD, xcd = wgid % NXCD, off = wgid / NXCD; wgid = (xcd < r ? xcd * (q + 1) : r * (q + 1) + (xcd - r) * q) + off; }
;         const int nig = wgm * nN, gid = wgid / nig, fm = gid * wgm, gsz = (nM - fm) < wgm ? (nM - fm) : wgm;
;         u.pm = fm + ((wgid % nig) % gsz); u.pn = (wgid % nig) / gsz; return true;
; template <class Epi, class Sched, bool ALIGN_EPI = false, bool SP2 = false>
; __device__ __forceinline__ void gemm_phase(PG8_LAS unsigned char* lds, const Gemm g, const Sched& S, const Epi& E, const int tid_in) {
;     const int tid = tid_in, wid = __builtin_amdgcn_readfirstlane(tid >> 6), lane = tid & 63, wr = wid >> 2, wc = wid & 3, fr = lane & 15, fq = lane >> 4;
;     const int K = g.K, nt = K / BK;
;     unsigned voffA[2], voffB[2];
; #pragma unroll
;     for (int i = 0; i < 2; ++i) { int R, C; stage_rc(tid * 16 + i * 8192, R, C); const int Rb = Epi::PERM ? ((R & ~31) + perm32(R & 31)) : R;
;         voffA[i] = (unsigned)(R * K + C) * 2u; voffB[i] = (unsigned)(Rb * K + C) * 2u; }
;     const size_t kstep = (size_t)(BK * 2);
;     const size_t hstep = (size_t)HALF * K * 2;
;     const size_t tstep = 2 * hstep;
;     const unsigned ldsw = (unsigned)wid * 1024u;
;     const int aoff = lds_byte(wr * 64 + fr, fq * 8), boff = lds_byte(wc * 32 + fr, fq * 8);
;     ...
;     Unit cur, nxt; int ui = 0;
;     if (!S.next(0, cur)) return;
;     f32x4 acc[2][2][4][2];
; #pragma unroll
;     for (int a = 0; a < 2; ++a)
; #pragma unroll
;         for (int b = 0; b < 2; ++b)
; #pragma unroll
;             for (int m = 0; m < 4; ++m)
; #pragma unroll
;                 for (int n = 0; n < 2; ++n) acc[a][b][m][n] = (f32x4){0.f, 0.f, 0.f, 0.f};
;     bf16x8 At[4][2], B0[2][2], B1[2][2];
;     const char* cA = (const char*)g.asel(cur.pn) + (size_t)cur.pm * tstep; const char* cB = (const char*)g.Bt + (size_t)cur.pn * tstep;
;     S.a_ready(cur);
;     if constexpr (SP2) {
;         PG8_STAGE(PG8_SB(0, 0), cB, voffB); PG8_STAGE(PG8_SB(0, 1), cB + hstep, voffB); PG8_STAGE(PG8_SA(0, 0), cA, voffA); PG8_STAGE(PG8_SA(0, 1), cA + hstep, voffA);
;         if (wr == 1) PG8_BAR;
.LBB0_302:
	v_readlane_b32 s2, v254, 1
	v_readlane_b32 s3, v254, 2
	s_cmp_lt_i32 s2, 4
	s_cselect_b64 s[2:3], -1, 0
	s_and_b64 s[4:5], s[2:3], s[0:1]
	s_andn2_b64 vcc, exec, s[4:5]
	s_cbranch_vccnz .LBB0_323
	v_readlane_b32 s98, v254, 3
	s_cmp_ge_u32 s98, 0x100
	s_cbranch_scc0 .Lmy_prio_3
	s_setprio 1
.Lmy_prio_3:
	v_mbcnt_lo_u32_b32 v8, -1, 0
	v_mbcnt_hi_u32_b32 v8, -1, v8
	s_cmpk_gt_i32 s84, 0x1ff
	v_add_u32_e32 v0, s52, v8
	s_mov_b64 s[0:1], s[82:83]
	v_readfirstlane_b32 s15, v0
	s_cbranch_scc1 .LBB0_323
	v_lshlrev_b32_e32 v1, 4, v0
	v_add_u32_e32 v2, 0x2000, v1
	v_ashrrev_i32_e32 v3, 31, v2
	v_lshrrev_b32_e32 v3, 22, v3
	v_add_u32_e32 v3, v2, v3
	v_ashrrev_i32_e32 v9, 10, v3
	v_mul_i32_i24_e32 v3, 0x400, v9
	v_sub_u32_e32 v2, v2, v3
	v_lshrrev_b32_e32 v3, 4, v2
	v_bitop3_b32 v2, v3, v2, 32 bitop3:0x6c
	v_ashrrev_i32_e32 v3, 31, v2
	v_lshrrev_b32_e32 v3, 26, v3
	v_add_u32_e32 v3, v2, v3
	v_lshlrev_b32_e32 v4, 3, v9
	v_ashrrev_i32_e32 v10, 6, v3
	v_and_b32_e32 v4, -16, v4
	v_add_u32_e32 v4, v10, v4
	s_load_dwordx2 s[2:3], s[0:1], 0xc8
	s_load_dwordx2 s[6:7], s[0:1], 0x0
	v_and_b32_e32 v5, 3, v10
	s_mov_b32 s0, 0x1fffe0
	v_lshrrev_b32_e32 v6, 2, v4
	v_lshlrev_b32_e32 v7, 1, v4
	v_and_b32_e32 v3, 0xc0, v3
	v_and_or_b32 v5, v4, s0, v5
	v_and_b32_e32 v6, 4, v6
	v_and_b32_e32 v7, 24, v7
	v_sub_u32_e32 v2, v2, v3
	v_mov_b32_e32 v3, 1
	v_or3_b32 v5, v5, v6, v7
	v_lshlrev_b32_e32 v6, 5, v9
	v_ashrrev_i16_sdwa v2, v3, sext(v2) dst_sel:DWORD dst_unused:UNUSED_PAD src0_sel:DWORD src1_sel:BYTE_0
	v_and_b32_e32 v6, 32, v6
	v_bfe_i32 v11, v2, 0, 16
	v_add_lshl_u32 v2, v6, v11, 1
	v_lshl_add_u32 v128, v5, 11, v2
	v_lshl_add_u32 v130, v4, 11, v2
	v_bfe_i32 v2, v0, 27, 1
	v_lshrrev_b32_e32 v2, 22, v2
	v_add_u32_e32 v2, v1, v2
	v_and_b32_e32 v2, 0xfffffc00, v2
	v_sub_u32_e32 v1, v1, v2
	v_lshrrev_b32_e32 v2, 4, v1
	v_ashrrev_i32_e32 v4, 31, v0
	v_bitop3_b32 v1, v2, v1, 32 bitop3:0x6c
	v_lshrrev_b32_e32 v4, 26, v4
	v_ashrrev_i32_e32 v2, 31, v1
	v_add_u32_e32 v0, v0, v4
	s_waitcnt lgkmcnt(0)
	s_add_u32 s33, s2, 0x4000000
	v_lshrrev_b32_e32 v2, 26, v2
	v_ashrrev_i32_e32 v13, 6, v0
	s_addc_u32 s40, s3, 0
	v_add_u32_e32 v2, v1, v2
	v_lshlrev_b32_e32 v0, 3, v13
	s_add_u32 s41, s2, 0x500000
	v_ashrrev_i32_e32 v12, 6, v2
	v_and_b32_e32 v0, -16, v0
	s_addc_u32 s42, s3, 0
	v_add_u32_e32 v0, v12, v0
	v_and_b32_e32 v4, 3, v12
	s_ashr_i32 s44, s84, 31
	v_and_or_b32 v4, v0, s0, v4
	s_lshr_b32 s0, s44, 29
	s_add_i32 s0, s84, s0
	s_and_b32 s1, s0, -8
	s_ashr_i32 s12, s15, 6
	s_sub_i32 s1, s84, s1
	s_ashr_i32 s16, s15, 8
	s_lshl_b32 s43, s12, 10
	s_lshl_b32 s9, s1, 6
	s_ashr_i32 s0, s0, 3
	s_mul_i32 s8, s1, 0x41
	s_cmp_lt_i32 s1, 0
	s_cselect_b32 s1, s8, s9
	s_add_i32 s1, s1, s0
	s_mul_hi_i32 s0, s1, 0x2aaaaaab
	s_lshr_b32 s8, s0, 31
	s_ashr_i32 s0, s0, 3
	v_lshrrev_b32_e32 v5, 2, v0
	v_lshlrev_b32_e32 v6, 1, v0
	v_and_b32_e32 v2, 0xc0, v2
	s_add_i32 s0, s0, s8
	v_and_b32_e32 v5, 4, v5
	v_and_b32_e32 v6, 24, v6
	v_sub_u32_e32 v1, v1, v2
	s_mul_i32 s8, s0, 12
	v_or3_b32 v4, v4, v5, v6
	v_lshlrev_b32_e32 v5, 5, v13
	v_ashrrev_i16_sdwa v1, v3, sext(v1) dst_sel:DWORD dst_unused:UNUSED_PAD src0_sel:DWORD src1_sel:BYTE_0
	s_sub_i32 s9, 0x80, s8
	s_mul_i32 s0, s0, 48
	v_and_b32_e32 v5, 32, v5
	v_bfe_i32 v14, v1, 0, 16
	s_min_u32 s9, s9, 12
	s_sub_i32 s10, s1, s0
	v_add_lshl_u32 v1, v5, v14, 1
	s_sext_i32_i8 s0, s10
	v_cvt_f32_ubyte0_e32 v3, s9
	v_lshl_add_u32 v132, v4, 11, v1
	v_cvt_f32_i32_e32 v2, s0
	v_rcp_iflag_f32_e32 v4, v3
	v_lshl_add_u32 v134, v0, 11, v1
	s_ashr_i32 s0, s0, 30
	s_or_b32 s11, s0, 1
	v_mul_f32_e32 v0, v2, v4
	v_trunc_f32_e32 v0, v0
	v_fma_f32 v1, -v0, v3, v2
	v_cvt_i32_f32_e32 v0, v0
	v_cmp_ge_f32_e64 s[0:1], |v1|, v3
	s_and_b64 s[0:1], s[0:1], exec
	s_cselect_b32 s0, s11, 0
	v_readfirstlane_b32 s1, v0
	s_add_i32 s14, s1, s0
	s_mul_i32 s0, s14, s9
	s_sub_i32 s0, s10, s0
	s_sext_i32_i8 s0, s0
	s_add_i32 s34, s8, s0
	s_ashr_i32 s35, s34, 31
	s_bfe_i64 s[8:9], s[14:15], 0x80000
	s_lshl_b64 s[0:1], s[34:35], 19
	s_lshl_b64 s[8:9], s[8:9], 19
	s_add_u32 s36, s41, s8
	s_addc_u32 s37, s42, s9
	s_add_i32 s35, s43, 0
	s_add_i32 m0, s35, 0x10000
	v_mov_b32_e32 v133, 0
	global_load_lds_dwordx4 v132, s[36:37]
	s_add_i32 m0, s35, 0x12000
	s_add_u32 s8, s36, 0x40000
	global_load_lds_dwordx4 v128, s[36:37]
	s_addc_u32 s9, s37, 0
	s_add_i32 m0, s35, 0x14000
	v_mov_b32_e32 v129, v133
	global_load_lds_dwordx4 v132, s[8:9]
	s_add_i32 m0, s35, 0x16000
	s_add_u32 s0, s33, s0
	s_addc_u32 s1, s40, s1
	s_add_i32 s45, s35, 0x2000
	global_load_lds_dwordx4 v128, s[8:9]
	s_mov_b32 m0, s35
	s_add_u32 s8, s0, 0x40000
	global_load_lds_dwordx4 v134, s[0:1]
	s_mov_b32 m0, s45
	s_addc_u32 s9, s1, 0
	s_add_i32 s46, s35, 0x4000
	global_load_lds_dwordx4 v130, s[0:1]
	s_mov_b32 m0, s46
	s_add_i32 s47, s35, 0x6000
	global_load_lds_dwordx4 v134, s[8:9]
	s_mov_b32 m0, s47
	v_mov_b32_e32 v135, v133
	global_load_lds_dwordx4 v130, s[8:9]
	v_mov_b32_e32 v131, v133
	s_cmp_eq_u32 s16, 1
	s_mov_b32 s48, 0
	v_lshl_add_u64 v[6:7], s[36:37], 0, v[132:133]
	v_lshl_add_u64 v[4:5], s[36:37], 0, v[128:129]
	v_lshl_add_u64 v[0:1], s[0:1], 0, v[134:135]
	s_cselect_b64 s[8:9], -1, 0
	s_cmp_lg_u32 s16, 1
	v_lshl_add_u64 v[2:3], s[0:1], 0, v[130:131]
	s_cbranch_scc1 .LBB0_306
	s_barrier

; __device__ __forceinline__ unsigned xb_ld(unsigned* p)              { return __hip_atomic_load(p, __ATOMIC_RELAXED, __HIP_MEMORY_SCOPE_AGENT); }
; __device__ __forceinline__ unsigned xb_add(unsigned* p, unsigned v) { return __hip_atomic_fetch_add(p, v, __ATOMIC_RELAXED, __HIP_MEMORY_SCOPE_AGENT); }
; __device__ __forceinline__ void xcd_barrier_complete(unsigned* bar, unsigned x, unsigned& nloc, unsigned& nx) {
;     const unsigned G = gridDim.x * gridDim.y * gridDim.z;
;     unsigned sum, cnt, mine, sp = 0u;
;     for (;;) {
;         sum = 0u; cnt = 0u; mine = 0u;
; #pragma unroll
;         for (unsigned j = 0; j < 16; ++j) { const unsigned c = xb_ld(&bar[XB_XCNT(j)]); sum += c; cnt += (c > 0u) ? 1u : 0u; mine = (j == x) ? c : mine; }
; __device__ __forceinline__ void xcd_barrier(const XcdBarrier& b, const int tid_) {
;     asm volatile("s_waitcnt vmcnt(0)" ::: "memory");
;     __syncthreads();
;     if (tid_ == 0) {
;         unsigned* bar = b.bar;
;         __builtin_amdgcn_s_waitcnt(0);
;         unsigned nloc = b.st[0], nx = b.st[1];
;         if (nloc == 0u) { xcd_barrier_complete(bar, b.x, nloc, nx); b.st[0] = nloc; b.st[1] = nx; }
;         const unsigned old = xb_add(&bar[XB_XSUB(b.x)], 1u);
.LBB0_323:
	s_setprio 0
	v_readlane_b32 s0, v254, 1
	v_readlane_b32 s1, v254, 2
	s_cmp_gt_i32 s1, 4
	s_cselect_b64 s[0:1], -1, 0
	s_and_b64 s[2:3], s[4:5], s[0:1]
	s_andn2_b64 vcc, exec, s[2:3]
	s_cbranch_vccnz .LBB0_377
	s_mov_b64 s[4:5], s[82:83]
	v_mbcnt_lo_u32_b32 v0, -1, 0
	v_mbcnt_hi_u32_b32 v0, -1, v0
	s_getreg_b32 s6, hwreg(HW_REG_XCC_ID, 0, 4)
	s_waitcnt vmcnt(0)
	v_sub_u32_e32 v0, 0, v0
	v_cmp_eq_u32_e32 vcc, s52, v0
	s_waitcnt vmcnt(0) lgkmcnt(0)
	s_barrier
	s_and_saveexec_b64 s[2:3], vcc
	s_cbranch_execz .LBB0_376
	s_add_i32 s7, 0, 0x23fc0
	v_mov_b32_e32 v0, s7
	s_load_dwordx2 s[4:5], s[4:5], 0xc8
	s_waitcnt vmcnt(0) expcnt(0) lgkmcnt(0)
	ds_read_b32 v2, v0
	s_add_i32 s7, 0, 0x23fc4
	v_mov_b32_e32 v0, s7
	ds_read_b32 v0, v0
	s_and_b32 s33, s6, 15
	s_waitcnt lgkmcnt(1)
	v_cmp_ne_u32_e32 vcc, 0, v2
	s_cbranch_vccnz .LBB0_340
	s_load_dword s6, s[82:83], 0xe0
	s_mov_b32 s49, 1
	v_mov_b32_e32 v16, 0
	s_waitcnt lgkmcnt(0)
	s_mul_i32 s48, s55, s6
	s_add_u32 s6, s4, 0x1900200
	s_addc_u32 s7, s5, 0
	s_add_u32 s8, s4, 0x1900400
	s_addc_u32 s9, s5, 0
	s_add_u32 s10, s4, 0x1900500
	s_addc_u32 s11, s5, 0
	s_add_u32 s12, s4, 0x1900600
	s_addc_u32 s13, s5, 0
	s_add_u32 s14, s4, 0x1900700
	s_addc_u32 s15, s5, 0
	s_add_u32 s16, s4, 0x1900800
	s_addc_u32 s17, s5, 0
	s_add_u32 s18, s4, 0x1900900
	s_addc_u32 s19, s5, 0
	s_add_u32 s20, s4, 0x1900a00
	s_addc_u32 s21, s5, 0
	s_add_u32 s22, s4, 0x1900b00
	s_addc_u32 s23, s5, 0
	s_add_u32 s24, s4, 0x1900c00
	s_addc_u32 s25, s5, 0
	s_add_u32 s26, s4, 0x1900d00
	s_addc_u32 s27, s5, 0
	s_add_u32 s28, s4, 0x1900e00
	s_addc_u32 s29, s5, 0
	s_add_u32 s30, s4, 0x1900f00
	s_addc_u32 s31, s5, 0
	s_add_u32 s34, s4, 0x1901000
	s_addc_u32 s35, s5, 0
	s_add_u32 s36, s4, 0x1901100
	s_addc_u32 s37, s5, 0
	s_add_u32 s38, s4, 0x1901200
	s_addc_u32 s39, s5, 0
	s_add_u32 s40, s4, 0x1901300
	s_mul_i32 s48, s48, s54
	s_addc_u32 s41, s5, 0
	s_branch .LBB0_328

; #define PG8_BAR __builtin_amdgcn_s_barrier()
;     __host__ __device__ bool next(int i, Unit& u) const {
;         const long L = (long)i * G + c; if (L >= nwg) return false;
;         int wgid = (int)L; { const int q = nwg / NXCD, r = nwg % NXCD, xcd = wgid % NXCD, off = wgid / NXCD; wgid = (xcd < r ? xcd * (q + 1) : r * (q + 1) + (xcd - r) * q) + off; }
;         const int nig = wgm * nN, gid = wgid / nig, fm = gid * wgm, gsz = (nM - fm) < wgm ? (nM - fm) : wgm;
;         u.pm = fm + ((wgid % nig) % gsz); u.pn = (wgid % nig) / gsz; return true;
; template <class Epi, class Sched, bool ALIGN_EPI = false, bool SP2 = false>
; __device__ __forceinline__ void gemm_phase(PG8_LAS unsigned char* lds, const Gemm g, const Sched& S, const Epi& E, const int tid_in) {
;     const int tid = tid_in, wid = __builtin_amdgcn_readfirstlane(tid >> 6), lane = tid & 63, wr = wid >> 2, wc = wid & 3, fr = lane & 15, fq = lane >> 4;
;     const int K = g.K, nt = K / BK;
;     unsigned voffA[2], voffB[2];
; #pragma unroll
;     for (int i = 0; i < 2; ++i) { int R, C; stage_rc(tid * 16 + i * 8192, R, C); const int Rb = Epi::PERM ? ((R & ~31) + perm32(R & 31)) : R;
;         voffA[i] = (unsigned)(R * K + C) * 2u; voffB[i] = (unsigned)(Rb * K + C) * 2u; }
;     const size_t kstep = (size_t)(BK * 2);
;     const size_t hstep = (size_t)HALF * K * 2;
;     const size_t tstep = 2 * hstep;
;     const unsigned ldsw = (unsigned)wid * 1024u;
;     const int aoff = lds_byte(wr * 64 + fr, fq * 8), boff = lds_byte(wc * 32 + fr, fq * 8);
;     ...
;     Unit cur, nxt; int ui = 0;
;     if (!S.next(0, cur)) return;
;     f32x4 acc[2][2][4][2];
; #pragma unroll
;     for (int a = 0; a < 2; ++a)
; #pragma unroll
;         for (int b = 0; b < 2; ++b)
; #pragma unroll
;             for (int m = 0; m < 4; ++m)
; #pragma unroll
;                 for (int n = 0; n < 2; ++n) acc[a][b][m][n] = (f32x4){0.f, 0.f, 0.f, 0.f};
;     bf16x8 At[4][2], B0[2][2], B1[2][2];
;     const char* cA = (const char*)g.asel(cur.pn) + (size_t)cur.pm * tstep; const char* cB = (const char*)g.Bt + (size_t)cur.pn * tstep;
;     S.a_ready(cur);
;     if constexpr (SP2) {
;         PG8_STAGE(PG8_SB(0, 0), cB, voffB); PG8_STAGE(PG8_SB(0, 1), cB + hstep, voffB); PG8_STAGE(PG8_SA(0, 0), cA, voffA); PG8_STAGE(PG8_SA(0, 1), cA + hstep, voffA);
;         if (wr == 1) PG8_BAR;
.LBB0_377:
	v_readlane_b32 s2, v254, 1
	v_readlane_b32 s3, v254, 2
	s_cmp_lt_i32 s2, 5
	s_cselect_b64 s[2:3], -1, 0
	s_and_b64 s[4:5], s[2:3], s[0:1]
	s_andn2_b64 vcc, exec, s[4:5]
	s_cbranch_vccnz .LBB0_398
	v_readlane_b32 s98, v254, 3
	s_cmp_ge_u32 s98, 0x100
	s_cbranch_scc0 .Lmy_prio_4
	s_setprio 1
.Lmy_prio_4:
	v_mbcnt_lo_u32_b32 v8, -1, 0
	v_mbcnt_hi_u32_b32 v8, -1, v8
	s_cmpk_gt_i32 s84, 0x1ff
	v_add_u32_e32 v0, s52, v8
	s_mov_b64 s[0:1], s[82:83]
	v_readfirstlane_b32 s19, v0
	s_cbranch_scc1 .LBB0_398
	v_lshlrev_b32_e32 v1, 4, v0
	v_add_u32_e32 v2, 0x2000, v1
	v_ashrrev_i32_e32 v3, 31, v2
	v_lshrrev_b32_e32 v3, 22, v3
	v_add_u32_e32 v3, v2, v3
	v_ashrrev_i32_e32 v9, 10, v3
	v_mul_i32_i24_e32 v3, 0x400, v9
	v_sub_u32_e32 v2, v2, v3
	v_lshrrev_b32_e32 v3, 4, v2
	v_bitop3_b32 v2, v3, v2, 32 bitop3:0x6c
	v_ashrrev_i32_e32 v3, 31, v2
	v_lshrrev_b32_e32 v3, 26, v3
	v_add_u32_e32 v3, v2, v3
	v_lshlrev_b32_e32 v4, 3, v9
	v_ashrrev_i32_e32 v10, 6, v3
	v_and_b32_e32 v4, -16, v4
	v_add_u32_e32 v4, v10, v4
	s_load_dwordx2 s[2:3], s[0:1], 0xc8
	v_and_b32_e32 v5, 3, v10
	s_mov_b32 s0, 0x1fffe0
	v_lshrrev_b32_e32 v6, 2, v4
	v_lshlrev_b32_e32 v7, 1, v4
	v_and_b32_e32 v3, 0xc0, v3
	v_and_or_b32 v5, v4, s0, v5
	v_and_b32_e32 v6, 4, v6
	v_and_b32_e32 v7, 24, v7
	v_sub_u32_e32 v2, v2, v3
	v_mov_b32_e32 v3, 1
	v_or3_b32 v5, v5, v6, v7
	v_lshlrev_b32_e32 v6, 5, v9
	v_ashrrev_i16_sdwa v2, v3, sext(v2) dst_sel:DWORD dst_unused:UNUSED_PAD src0_sel:DWORD src1_sel:BYTE_0
	v_and_b32_e32 v6, 32, v6
	v_bfe_i32 v11, v2, 0, 16
	v_add_lshl_u32 v2, v6, v11, 1
	v_lshl_add_u32 v128, v5, 11, v2
	v_lshl_add_u32 v130, v4, 11, v2
	v_bfe_i32 v2, v0, 27, 1
	v_lshrrev_b32_e32 v2, 22, v2
	v_add_u32_e32 v2, v1, v2
	v_and_b32_e32 v2, 0xfffffc00, v2
	v_sub_u32_e32 v1, v1, v2
	v_lshrrev_b32_e32 v2, 4, v1
	v_ashrrev_i32_e32 v4, 31, v0
	v_bitop3_b32 v1, v2, v1, 32 bitop3:0x6c
	v_lshrrev_b32_e32 v4, 26, v4
	v_ashrrev_i32_e32 v2, 31, v1
	v_add_u32_e32 v0, v0, v4
	s_waitcnt lgkmcnt(0)
	s_add_u32 s6, s2, 0x16000000
	v_lshrrev_b32_e32 v2, 26, v2
	v_ashrrev_i32_e32 v13, 6, v0
	s_addc_u32 s7, s3, 0
	v_add_u32_e32 v2, v1, v2
	v_lshlrev_b32_e32 v0, 3, v13
	s_add_u32 s33, s2, 0x700000
	v_ashrrev_i32_e32 v12, 6, v2
	v_and_b32_e32 v0, -16, v0
	s_addc_u32 s42, s3, 0
	v_add_u32_e32 v0, v12, v0
	v_and_b32_e32 v4, 3, v12
	s_ashr_i32 s44, s84, 31
	v_and_or_b32 v4, v0, s0, v4
	s_lshr_b32 s0, s44, 29
	s_add_i32 s0, s84, s0
	s_and_b32 s1, s0, -8
	s_ashr_i32 s16, s19, 6
	s_sub_i32 s1, s84, s1
	s_ashr_i32 s20, s19, 8
	s_lshl_b32 s43, s16, 10
	s_lshl_b32 s9, s1, 6
	s_ashr_i32 s0, s0, 3
	s_mul_i32 s8, s1, 0x41
	s_cmp_lt_i32 s1, 0
	s_cselect_b32 s1, s8, s9
	s_add_i32 s1, s1, s0
	s_mul_hi_i32 s0, s1, 0x2aaaaaab
	s_lshr_b32 s8, s0, 31
	s_ashr_i32 s0, s0, 3
	v_lshrrev_b32_e32 v5, 2, v0
	v_lshlrev_b32_e32 v6, 1, v0
	v_and_b32_e32 v2, 0xc0, v2
	s_add_i32 s0, s0, s8
	v_and_b32_e32 v5, 4, v5
	v_and_b32_e32 v6, 24, v6
	v_sub_u32_e32 v1, v1, v2
	s_mul_i32 s8, s0, 12
	v_or3_b32 v4, v4, v5, v6
	v_lshlrev_b32_e32 v5, 5, v13
	v_ashrrev_i16_sdwa v1, v3, sext(v1) dst_sel:DWORD dst_unused:UNUSED_PAD src0_sel:DWORD src1_sel:BYTE_0
	s_sub_i32 s9, 0x80, s8
	s_mul_i32 s0, s0, 48
	v_and_b32_e32 v5, 32, v5
	v_bfe_i32 v14, v1, 0, 16
	s_min_u32 s9, s9, 12
	s_sub_i32 s10, s1, s0
	v_add_lshl_u32 v1, v5, v14, 1
	s_sext_i32_i8 s0, s10
	v_cvt_f32_ubyte0_e32 v3, s9
	v_lshl_add_u32 v132, v4, 11, v1
	v_cvt_f32_i32_e32 v2, s0
	v_rcp_iflag_f32_e32 v4, v3
	v_lshl_add_u32 v134, v0, 11, v1
	s_ashr_i32 s0, s0, 30
	s_or_b32 s11, s0, 1
	v_mul_f32_e32 v0, v2, v4
	v_trunc_f32_e32 v0, v0
	v_fma_f32 v1, -v0, v3, v2
	v_cvt_i32_f32_e32 v0, v0
	v_cmp_ge_f32_e64 s[0:1], |v1|, v3
	s_and_b64 s[0:1], s[0:1], exec
	s_cselect_b32 s0, s11, 0
	v_readfirstlane_b32 s1, v0
	s_add_i32 s18, s1, s0
	s_mul_i32 s0, s18, s9
	s_sub_i32 s0, s10, s0
	s_sext_i32_i8 s0, s0
	s_add_i32 s36, s8, s0
	s_ashr_i32 s37, s36, 31
	s_bfe_i64 s[8:9], s[18:19], 0x80000
	s_lshl_b64 s[0:1], s[36:37], 19
	s_lshl_b64 s[8:9], s[8:9], 19
	s_add_u32 s38, s33, s8
	s_addc_u32 s39, s42, s9
	s_add_i32 s37, s43, 0
	s_add_i32 m0, s37, 0x10000
	v_mov_b32_e32 v133, 0
	global_load_lds_dwordx4 v132, s[38:39]
	s_add_i32 m0, s37, 0x12000
	s_add_u32 s8, s38, 0x40000
	global_load_lds_dwordx4 v128, s[38:39]
	s_addc_u32 s9, s39, 0
	s_add_i32 m0, s37, 0x14000
	v_mov_b32_e32 v129, v133
	global_load_lds_dwordx4 v132, s[8:9]
	s_add_i32 m0, s37, 0x16000
	s_add_u32 s0, s6, s0
	s_addc_u32 s1, s7, s1
	s_add_i32 s45, s37, 0x2000
	global_load_lds_dwordx4 v128, s[8:9]
	s_mov_b32 m0, s37
	s_add_u32 s8, s0, 0x40000
	global_load_lds_dwordx4 v134, s[0:1]
	s_mov_b32 m0, s45
	s_addc_u32 s9, s1, 0
	s_add_i32 s46, s37, 0x4000
	global_load_lds_dwordx4 v130, s[0:1]
	s_mov_b32 m0, s46
	s_add_i32 s47, s37, 0x6000
	global_load_lds_dwordx4 v134, s[8:9]
	s_mov_b32 m0, s47
	v_mov_b32_e32 v135, v133
	global_load_lds_dwordx4 v130, s[8:9]
	v_mov_b32_e32 v131, v133
	s_cmp_eq_u32 s20, 1
	s_mov_b32 s48, 0
	v_lshl_add_u64 v[6:7], s[38:39], 0, v[132:133]
	v_lshl_add_u64 v[2:3], s[38:39], 0, v[128:129]
	s_mov_b64 s[8:9], 0x40000
	v_lshl_add_u64 v[0:1], s[0:1], 0, v[134:135]
	s_cselect_b64 s[10:11], -1, 0
	s_cmp_lg_u32 s20, 1
	v_lshl_add_u64 v[4:5], s[0:1], 0, v[130:131]
	s_cbranch_scc1 .LBB0_381
	s_barrier

; __device__ __forceinline__ unsigned xb_ld(unsigned* p)              { return __hip_atomic_load(p, __ATOMIC_RELAXED, __HIP_MEMORY_SCOPE_AGENT); }
; __device__ __forceinline__ unsigned xb_add(unsigned* p, unsigned v) { return __hip_atomic_fetch_add(p, v, __ATOMIC_RELAXED, __HIP_MEMORY_SCOPE_AGENT); }
; __device__ __forceinline__ void xcd_barrier_complete(unsigned* bar, unsigned x, unsigned& nloc, unsigned& nx) {
;     const unsigned G = gridDim.x * gridDim.y * gridDim.z;
;     unsigned sum, cnt, mine, sp = 0u;
;     for (;;) {
;         sum = 0u; cnt = 0u; mine = 0u;
; #pragma unroll
;         for (unsigned j = 0; j < 16; ++j) { const unsigned c = xb_ld(&bar[XB_XCNT(j)]); sum += c; cnt += (c > 0u) ? 1u : 0u; mine = (j == x) ? c : mine; }
; __device__ __forceinline__ void xcd_barrier(const XcdBarrier& b, const int tid_) {
;     asm volatile("s_waitcnt vmcnt(0)" ::: "memory");
;     __syncthreads();
;     if (tid_ == 0) {
;         unsigned* bar = b.bar;
;         __builtin_amdgcn_s_waitcnt(0);
;         unsigned nloc = b.st[0], nx = b.st[1];
;         if (nloc == 0u) { xcd_barrier_complete(bar, b.x, nloc, nx); b.st[0] = nloc; b.st[1] = nx; }
;         const unsigned old = xb_add(&bar[XB_XSUB(b.x)], 1u);
.LBB0_398:
	s_setprio 0
	v_readlane_b32 s0, v254, 1
	v_readlane_b32 s1, v254, 2
	s_cmp_gt_i32 s1, 5
	s_cselect_b64 s[0:1], -1, 0
	s_and_b64 s[2:3], s[4:5], s[0:1]
	s_andn2_b64 vcc, exec, s[2:3]
	s_cbranch_vccnz .LBB0_452
	s_mov_b64 s[4:5], s[82:83]
	v_mbcnt_lo_u32_b32 v0, -1, 0
	v_mbcnt_hi_u32_b32 v0, -1, v0
	s_getreg_b32 s6, hwreg(HW_REG_XCC_ID, 0, 4)
	s_waitcnt vmcnt(0)
	v_sub_u32_e32 v0, 0, v0
	v_cmp_eq_u32_e32 vcc, s52, v0
	s_waitcnt vmcnt(0) lgkmcnt(0)
	s_barrier
	s_and_saveexec_b64 s[2:3], vcc
	s_cbranch_execz .LBB0_451
	s_add_i32 s7, 0, 0x23fc0
	v_mov_b32_e32 v0, s7
	s_load_dwordx2 s[4:5], s[4:5], 0xc8
	s_waitcnt vmcnt(0) expcnt(0) lgkmcnt(0)
	ds_read_b32 v2, v0
	s_add_i32 s7, 0, 0x23fc4
	v_mov_b32_e32 v0, s7
	ds_read_b32 v0, v0
	s_and_b32 s33, s6, 15
	s_waitcnt lgkmcnt(1)
	v_cmp_ne_u32_e32 vcc, 0, v2
	s_cbranch_vccnz .LBB0_415
	s_load_dword s6, s[82:83], 0xe0
	s_mov_b32 s49, 1
	v_mov_b32_e32 v16, 0
	s_waitcnt lgkmcnt(0)
	s_mul_i32 s48, s55, s6
	s_add_u32 s6, s4, 0x1900200
	s_addc_u32 s7, s5, 0
	s_add_u32 s8, s4, 0x1900400
	s_addc_u32 s9, s5, 0
	s_add_u32 s10, s4, 0x1900500
	s_addc_u32 s11, s5, 0
	s_add_u32 s12, s4, 0x1900600
	s_addc_u32 s13, s5, 0
	s_add_u32 s14, s4, 0x1900700
	s_addc_u32 s15, s5, 0
	s_add_u32 s16, s4, 0x1900800
	s_addc_u32 s17, s5, 0
	s_add_u32 s18, s4, 0x1900900
	s_addc_u32 s19, s5, 0
	s_add_u32 s20, s4, 0x1900a00
	s_addc_u32 s21, s5, 0
	s_add_u32 s22, s4, 0x1900b00
	s_addc_u32 s23, s5, 0
	s_add_u32 s24, s4, 0x1900c00
	s_addc_u32 s25, s5, 0
	s_add_u32 s26, s4, 0x1900d00
	s_addc_u32 s27, s5, 0
	s_add_u32 s28, s4, 0x1900e00
	s_addc_u32 s29, s5, 0
	s_add_u32 s30, s4, 0x1900f00
	s_addc_u32 s31, s5, 0
	s_add_u32 s34, s4, 0x1901000
	s_addc_u32 s35, s5, 0
	s_add_u32 s36, s4, 0x1901100
	s_addc_u32 s37, s5, 0
	s_add_u32 s38, s4, 0x1901200
	s_addc_u32 s39, s5, 0
	s_add_u32 s40, s4, 0x1901300
	s_mul_i32 s48, s48, s54
	s_addc_u32 s41, s5, 0
	s_branch .LBB0_403

; #define PG8_BAR __builtin_amdgcn_s_barrier()
;     __host__ __device__ bool next(int i, Unit& u) const {
;         const long L = (long)i * G + c; if (L >= nwg) return false;
;         int wgid = (int)L; { const int q = nwg / NXCD, r = nwg % NXCD, xcd = wgid % NXCD, off = wgid / NXCD; wgid = (xcd < r ? xcd * (q + 1) : r * (q + 1) + (xcd - r) * q) + off; }
;         const int nig = wgm * nN, gid = wgid / nig, fm = gid * wgm, gsz = (nM - fm) < wgm ? (nM - fm) : wgm;
;         u.pm = fm + ((wgid % nig) % gsz); u.pn = (wgid % nig) / gsz; return true;
; template <class Epi, class Sched, bool ALIGN_EPI = false, bool SP2 = false>
; __device__ __forceinline__ void gemm_phase(PG8_LAS unsigned char* lds, const Gemm g, const Sched& S, const Epi& E, const int tid_in) {
;     const int tid = tid_in, wid = __builtin_amdgcn_readfirstlane(tid >> 6), lane = tid & 63, wr = wid >> 2, wc = wid & 3, fr = lane & 15, fq = lane >> 4;
;     const int K = g.K, nt = K / BK;
;     unsigned voffA[2], voffB[2];
; #pragma unroll
;     for (int i = 0; i < 2; ++i) { int R, C; stage_rc(tid * 16 + i * 8192, R, C); const int Rb = Epi::PERM ? ((R & ~31) + perm32(R & 31)) : R;
;         voffA[i] = (unsigned)(R * K + C) * 2u; voffB[i] = (unsigned)(Rb * K + C) * 2u; }
;     const size_t kstep = (size_t)(BK * 2);
;     const size_t hstep = (size_t)HALF * K * 2;
;     const size_t tstep = 2 * hstep;
;     const unsigned ldsw = (unsigned)wid * 1024u;
;     const int aoff = lds_byte(wr * 64 + fr, fq * 8), boff = lds_byte(wc * 32 + fr, fq * 8);
;     ...
;     Unit cur, nxt; int ui = 0;
;     if (!S.next(0, cur)) return;
;     f32x4 acc[2][2][4][2];
; #pragma unroll
;     for (int a = 0; a < 2; ++a)
; #pragma unroll
;         for (int b = 0; b < 2; ++b)
; #pragma unroll
;             for (int m = 0; m < 4; ++m)
; #pragma unroll
;                 for (int n = 0; n < 2; ++n) acc[a][b][m][n] = (f32x4){0.f, 0.f, 0.f, 0.f};
;     bf16x8 At[4][2], B0[2][2], B1[2][2];
;     const char* cA = (const char*)g.asel(cur.pn) + (size_t)cur.pm * tstep; const char* cB = (const char*)g.Bt + (size_t)cur.pn * tstep;
;     S.a_ready(cur);
;     if constexpr (SP2) {
;         PG8_STAGE(PG8_SB(0, 0), cB, voffB); PG8_STAGE(PG8_SB(0, 1), cB + hstep, voffB); PG8_STAGE(PG8_SA(0, 0), cA, voffA); PG8_STAGE(PG8_SA(0, 1), cA + hstep, voffA);
;         if (wr == 1) PG8_BAR;
.LBB0_521:
	v_readlane_b32 s0, v254, 1
	v_readlane_b32 s1, v254, 2
	s_cmp_lt_i32 s0, 7
	s_cselect_b64 s[0:1], -1, 0
	s_and_b64 s[8:9], s[0:1], s[2:3]
	s_andn2_b64 vcc, exec, s[8:9]
	s_cbranch_vccnz .LBB0_562
	v_readlane_b32 s98, v254, 3
	s_cmp_ge_u32 s98, 0x100
	s_cbranch_scc0 .Lmy_prio_6
	s_setprio 1
.Lmy_prio_6:
	v_mbcnt_lo_u32_b32 v0, -1, 0
	v_mbcnt_hi_u32_b32 v0, -1, v0
	s_ashr_i32 s42, s84, 31
	v_add_u32_e32 v157, s52, v0
	v_ashrrev_i32_e32 v2, 31, v157
	v_lshrrev_b32_e32 v2, 26, v2
	v_add_u32_e32 v2, v157, v2
	v_ashrrev_i32_e32 v146, 6, v2
	v_bfe_i32 v2, v157, 27, 1
	v_lshlrev_b32_e32 v1, 4, v157
	v_lshrrev_b32_e32 v2, 22, v2
	v_add_u32_e32 v2, v1, v2
	v_and_b32_e32 v2, 0xfffffc00, v2
	v_sub_u32_e32 v2, v1, v2
	v_lshrrev_b32_e32 v3, 4, v2
	v_bitop3_b32 v2, v3, v2, 32 bitop3:0x6c
	v_ashrrev_i32_e32 v4, 31, v2
	v_lshrrev_b32_e32 v4, 26, v4
	v_add_u32_e32 v4, v2, v4
	v_lshlrev_b32_e32 v3, 3, v146
	v_ashrrev_i32_e32 v147, 6, v4
	v_and_b32_e32 v4, 0xc0, v4
	v_and_b32_e32 v3, -16, v3
	v_sub_u32_e32 v2, v2, v4
	v_mov_b32_e32 v4, 1
	v_add_u32_e32 v156, v147, v3
	v_lshlrev_b32_e32 v3, 5, v146
	v_ashrrev_i16_sdwa v2, v4, sext(v2) dst_sel:DWORD dst_unused:UNUSED_PAD src0_sel:DWORD src1_sel:BYTE_0
	v_and_b32_e32 v3, 32, v3
	v_bfe_i32 v148, v2, 0, 16
	v_add_u32_e32 v2, v3, v148
	v_lshlrev_b32_e32 v3, 1, v156
	v_and_b32_e32 v158, 24, v3
	v_lshrrev_b32_e32 v3, 2, v156
	v_add_u32_e32 v1, 0x2000, v1
	v_and_b32_e32 v159, 4, v3
	v_ashrrev_i32_e32 v3, 31, v1
	v_lshrrev_b32_e32 v3, 22, v3
	v_add_u32_e32 v3, v1, v3
	v_ashrrev_i32_e32 v149, 10, v3
	v_mul_i32_i24_e32 v3, 0x400, v149
	v_sub_u32_e32 v1, v1, v3
	v_lshrrev_b32_e32 v3, 4, v1
	v_bitop3_b32 v1, v3, v1, 32 bitop3:0x6c
	v_ashrrev_i32_e32 v5, 31, v1
	v_lshrrev_b32_e32 v5, 26, v5
	v_add_u32_e32 v5, v1, v5
	v_lshlrev_b32_e32 v3, 3, v149
	v_ashrrev_i32_e32 v150, 6, v5
	v_and_b32_e32 v5, 0xc0, v5
	s_lshr_b32 s0, s42, 29
	v_and_b32_e32 v3, -16, v3
	v_sub_u32_e32 v1, v1, v5
	s_add_i32 s0, s84, s0
	v_add_u32_e32 v161, v150, v3
	v_lshlrev_b32_e32 v3, 5, v149
	v_ashrrev_i16_sdwa v1, v4, sext(v1) dst_sel:DWORD dst_unused:UNUSED_PAD src0_sel:DWORD src1_sel:BYTE_0
	s_ashr_i32 s43, s0, 3
	s_and_b32 s0, s0, -8
	v_and_b32_e32 v3, 32, v3
	v_bfe_i32 v151, v1, 0, 16
	s_sub_i32 s44, s84, s0
	s_mov_b64 s[0:1], s[82:83]
	v_add_u32_e32 v1, v3, v151
	v_lshlrev_b32_e32 v3, 1, v161
	s_load_dwordx4 s[4:7], s[0:1], 0xc0
	v_and_b32_e32 v163, 24, v3
	v_lshrrev_b32_e32 v3, 2, v161
	v_and_b32_e32 v164, 4, v3
	v_lshrrev_b32_e32 v3, 1, v0
	s_ashr_i32 s33, s54, 31
	v_and_b32_e32 v153, 15, v0
	v_and_b32_e32 v152, 24, v3
	v_lshlrev_b32_e32 v0, 2, v0
	s_cmp_lt_i32 s44, 0
	v_lshlrev_b32_e32 v154, 1, v152
	v_lshlrev_b32_e32 v3, 6, v153
	v_and_b32_e32 v0, 32, v0
	s_waitcnt lgkmcnt(0)
	s_cselect_b64 s[10:11], -1, 0
	s_cmpk_gt_i32 s84, 0x3ff
	v_readfirstlane_b32 s2, v157
	v_and_b32_e32 v160, 3, v147
	v_and_b32_e32 v165, 3, v150
	v_bitop3_b32 v155, v154, v0, v3 bitop3:0x36
	v_lshlrev_b32_e32 v166, 1, v1
	v_lshlrev_b32_e32 v162, 1, v2
	s_cbranch_scc1 .LBB0_542
	s_add_u32 s45, s6, 0x8000000
	s_addc_u32 s46, s7, 0
	s_add_u32 s47, s6, 0xd00000
	s_addc_u32 s48, s7, 0
	s_add_u32 s49, s6, 0xc000000
	s_mov_b32 s0, 0x1fffe0
	s_addc_u32 s50, s7, 0
	s_ashr_i32 s16, s2, 6
	v_and_or_b32 v0, v161, s0, v165
	s_ashr_i32 s3, s2, 8
	s_lshl_b32 s51, s16, 10
	v_or3_b32 v0, v0, v164, v163
	s_lshl_b32 s13, s44, 7
	v_lshl_add_u32 v128, v0, 11, v166
	v_and_or_b32 v0, v156, s0, v160
	s_mul_i32 s12, s44, 0x81
	s_and_b64 s[0:1], s[10:11], exec
	s_cselect_b32 s0, s12, s13
	s_add_i32 s0, s0, s43
	s_mul_hi_i32 s1, s0, 0x2aaaaaab
	s_lshr_b32 s12, s1, 31
	s_ashr_i32 s1, s1, 3
	s_add_i32 s1, s1, s12
	s_mul_i32 s12, s1, 6
	s_sub_i32 s13, 0x80, s12
	s_mul_i32 s1, s1, 48
	s_min_u32 s13, s13, 6
	s_sub_i32 s14, s0, s1
	v_or3_b32 v0, v0, v159, v158
	s_sext_i32_i8 s0, s14
	v_cvt_f32_ubyte0_e32 v1, s13
	v_lshl_add_u32 v132, v0, 11, v162
	v_cvt_f32_i32_e32 v0, s0
	v_rcp_iflag_f32_e32 v2, v1
	s_ashr_i32 s0, s0, 30
	s_or_b32 s15, s0, 1
	v_lshl_add_u32 v134, v156, 11, v162
	v_mul_f32_e32 v2, v0, v2
	v_trunc_f32_e32 v2, v2
	v_fma_f32 v0, -v2, v1, v0
	v_cvt_i32_f32_e32 v2, v2
	v_cmp_ge_f32_e64 s[0:1], |v0|, v1
	s_and_b64 s[0:1], s[0:1], exec
	s_cselect_b32 s0, s15, 0
	v_readfirstlane_b32 s1, v2
	s_add_i32 s0, s1, s0
	s_mul_i32 s13, s0, s13
	s_sub_i32 s13, s14, s13
	s_sext_i32_i8 s13, s13
	s_bfe_i32 s1, s0, 0x80000
	s_add_i32 s36, s12, s13
	s_sext_i32_i16 s68, s1
	s_ashr_i32 s37, s36, 31
	s_bfe_i64 s[0:1], s[0:1], 0x80000
	s_lshl_b64 s[12:13], s[36:37], 19
	s_lshl_b64 s[0:1], s[0:1], 19
	s_add_u32 s38, s47, s0
	s_addc_u32 s39, s48, s1
	s_add_i32 s37, s51, 0
	s_add_i32 m0, s37, 0x10000
	s_add_i32 s0, s37, 0x12000
	s_cmp_lt_i32 s68, 4
	global_load_lds_dwordx4 v132, s[38:39]
	s_mov_b32 m0, s0
	s_cselect_b32 s14, s46, s50
	s_cselect_b32 s15, s45, s49
	s_add_u32 s0, s38, 0x40000
	global_load_lds_dwordx4 v128, s[38:39]
	s_addc_u32 s1, s39, 0
	s_add_i32 m0, s37, 0x14000
	v_lshl_add_u32 v130, v161, 11, v166
	global_load_lds_dwordx4 v132, s[0:1]
	s_add_i32 m0, s37, 0x16000
	v_mov_b32_e32 v133, 0
	global_load_lds_dwordx4 v128, s[0:1]
	s_add_u32 s0, s15, s12
	s_addc_u32 s1, s14, s13
	s_add_i32 s52, s37, 0x2000
	s_mov_b32 m0, s37
	s_add_u32 s12, s0, 0x40000
	global_load_lds_dwordx4 v134, s[0:1]
	s_mov_b32 m0, s52
	s_addc_u32 s13, s1, 0
	s_add_i32 s53, s37, 0x4000
	global_load_lds_dwordx4 v130, s[0:1]
	s_mov_b32 m0, s53
	s_add_i32 s56, s37, 0x6000
	global_load_lds_dwordx4 v134, s[12:13]
	s_mov_b32 m0, s56
	v_mov_b32_e32 v129, v133
	global_load_lds_dwordx4 v130, s[12:13]
	v_mov_b32_e32 v135, v133
	v_mov_b32_e32 v131, v133
	s_cmp_eq_u32 s3, 1
	v_lshl_add_u64 v[6:7], s[38:39], 0, v[132:133]
	v_lshl_add_u64 v[2:3], s[38:39], 0, v[128:129]
	s_mov_b64 s[12:13], 0x40000
	v_lshl_add_u64 v[0:1], s[0:1], 0, v[134:135]
	s_cselect_b64 s[14:15], -1, 0
	s_cmp_lg_u32 s3, 1
	v_lshl_add_u64 v[4:5], s[0:1], 0, v[130:131]
	s_cbranch_scc1 .LBB0_525
	s_barrier

; __device__ __forceinline__ unsigned xb_ld(unsigned* p)              { return __hip_atomic_load(p, __ATOMIC_RELAXED, __HIP_MEMORY_SCOPE_AGENT); }
; __device__ __forceinline__ unsigned xb_add(unsigned* p, unsigned v) { return __hip_atomic_fetch_add(p, v, __ATOMIC_RELAXED, __HIP_MEMORY_SCOPE_AGENT); }
; __device__ __forceinline__ void xcd_barrier_complete(unsigned* bar, unsigned x, unsigned& nloc, unsigned& nx) {
;     const unsigned G = gridDim.x * gridDim.y * gridDim.z;
;     unsigned sum, cnt, mine, sp = 0u;
;     for (;;) {
;         sum = 0u; cnt = 0u; mine = 0u;
; #pragma unroll
;         for (unsigned j = 0; j < 16; ++j) { const unsigned c = xb_ld(&bar[XB_XCNT(j)]); sum += c; cnt += (c > 0u) ? 1u : 0u; mine = (j == x) ? c : mine; }
; __device__ __forceinline__ void xcd_barrier(const XcdBarrier& b, const int tid_) {
;     asm volatile("s_waitcnt vmcnt(0)" ::: "memory");
;     __syncthreads();
;     if (tid_ == 0) {
;         unsigned* bar = b.bar;
;         __builtin_amdgcn_s_waitcnt(0);
;         unsigned nloc = b.st[0], nx = b.st[1];
;         if (nloc == 0u) { xcd_barrier_complete(bar, b.x, nloc, nx); b.st[0] = nloc; b.st[1] = nx; }
;         const unsigned old = xb_add(&bar[XB_XSUB(b.x)], 1u);
.LBB0_562:
	s_setprio 0
	v_readlane_b32 s0, v254, 1
	v_readlane_b32 s1, v254, 2
	s_cmp_gt_i32 s1, 7
	s_cselect_b64 s[0:1], -1, 0
	s_and_b64 s[2:3], s[8:9], s[0:1]
	s_andn2_b64 vcc, exec, s[2:3]
	s_cbranch_vccnz .LBB0_616
	s_mov_b64 s[4:5], s[82:83]
	v_mbcnt_lo_u32_b32 v0, -1, 0
	v_mbcnt_hi_u32_b32 v0, -1, v0
	s_getreg_b32 s6, hwreg(HW_REG_XCC_ID, 0, 4)
	s_waitcnt vmcnt(0)
	v_sub_u32_e32 v0, 0, v0
	v_cmp_eq_u32_e32 vcc, s52, v0
	s_waitcnt vmcnt(0) lgkmcnt(0)
	s_barrier
	s_and_saveexec_b64 s[2:3], vcc
	s_cbranch_execz .LBB0_615
	s_add_i32 s7, 0, 0x23fc0
	v_mov_b32_e32 v0, s7
	s_load_dwordx2 s[4:5], s[4:5], 0xc8
	s_waitcnt vmcnt(0) expcnt(0) lgkmcnt(0)
	ds_read_b32 v2, v0
	s_add_i32 s7, 0, 0x23fc4
	v_mov_b32_e32 v0, s7
	ds_read_b32 v0, v0
	s_and_b32 s33, s6, 15
	s_waitcnt lgkmcnt(1)
	v_cmp_ne_u32_e32 vcc, 0, v2
	s_cbranch_vccnz .LBB0_579
	s_load_dword s6, s[82:83], 0xe0
	s_mov_b32 s49, 1
	v_mov_b32_e32 v16, 0
	s_waitcnt lgkmcnt(0)
	s_mul_i32 s48, s55, s6
	s_add_u32 s6, s4, 0x1900200
	s_addc_u32 s7, s5, 0
	s_add_u32 s8, s4, 0x1900400
	s_addc_u32 s9, s5, 0
	s_add_u32 s10, s4, 0x1900500
	s_addc_u32 s11, s5, 0
	s_add_u32 s12, s4, 0x1900600
	s_addc_u32 s13, s5, 0
	s_add_u32 s14, s4, 0x1900700
	s_addc_u32 s15, s5, 0
	s_add_u32 s16, s4, 0x1900800
	s_addc_u32 s17, s5, 0
	s_add_u32 s18, s4, 0x1900900
	s_addc_u32 s19, s5, 0
	s_add_u32 s20, s4, 0x1900a00
	s_addc_u32 s21, s5, 0
	s_add_u32 s22, s4, 0x1900b00
	s_addc_u32 s23, s5, 0
	s_add_u32 s24, s4, 0x1900c00
	s_addc_u32 s25, s5, 0
	s_add_u32 s26, s4, 0x1900d00
	s_addc_u32 s27, s5, 0
	s_add_u32 s28, s4, 0x1900e00
	s_addc_u32 s29, s5, 0
	s_add_u32 s30, s4, 0x1900f00
	s_addc_u32 s31, s5, 0
	s_add_u32 s34, s4, 0x1901000
	s_addc_u32 s35, s5, 0
	s_add_u32 s36, s4, 0x1901100
	s_addc_u32 s37, s5, 0
	s_add_u32 s38, s4, 0x1901200
	s_addc_u32 s39, s5, 0
	s_add_u32 s40, s4, 0x1901300
	s_mul_i32 s48, s48, s54
	s_addc_u32 s41, s5, 0
	s_branch .LBB0_567

; #define PG8_BAR __builtin_amdgcn_s_barrier()
;     __host__ __device__ bool next(int i, Unit& u) const {
;         const long L = (long)i * G + c; if (L >= nwg) return false;
;         int wgid = (int)L; { const int q = nwg / NXCD, r = nwg % NXCD, xcd = wgid % NXCD, off = wgid / NXCD; wgid = (xcd < r ? xcd * (q + 1) : r * (q + 1) + (xcd - r) * q) + off; }
;         const int nig = wgm * nN, gid = wgid / nig, fm = gid * wgm, gsz = (nM - fm) < wgm ? (nM - fm) : wgm;
;         u.pm = fm + ((wgid % nig) % gsz); u.pn = (wgid % nig) / gsz; return true;
; template <class Epi, class Sched, bool ALIGN_EPI = false, bool SP2 = false>
; __device__ __forceinline__ void gemm_phase(PG8_LAS unsigned char* lds, const Gemm g, const Sched& S, const Epi& E, const int tid_in) {
;     const int tid = tid_in, wid = __builtin_amdgcn_readfirstlane(tid >> 6), lane = tid & 63, wr = wid >> 2, wc = wid & 3, fr = lane & 15, fq = lane >> 4;
;     const int K = g.K, nt = K / BK;
;     unsigned voffA[2], voffB[2];
; #pragma unroll
;     for (int i = 0; i < 2; ++i) { int R, C; stage_rc(tid * 16 + i * 8192, R, C); const int Rb = Epi::PERM ? ((R & ~31) + perm32(R & 31)) : R;
;         voffA[i] = (unsigned)(R * K + C) * 2u; voffB[i] = (unsigned)(Rb * K + C) * 2u; }
;     const size_t kstep = (size_t)(BK * 2);
;     const size_t hstep = (size_t)HALF * K * 2;
;     const size_t tstep = 2 * hstep;
;     const unsigned ldsw = (unsigned)wid * 1024u;
;     const int aoff = lds_byte(wr * 64 + fr, fq * 8), boff = lds_byte(wc * 32 + fr, fq * 8);
;     ...
;     Unit cur, nxt; int ui = 0;
;     if (!S.next(0, cur)) return;
;     f32x4 acc[2][2][4][2];
; #pragma unroll
;     for (int a = 0; a < 2; ++a)
; #pragma unroll
;         for (int b = 0; b < 2; ++b)
; #pragma unroll
;             for (int m = 0; m < 4; ++m)
; #pragma unroll
;                 for (int n = 0; n < 2; ++n) acc[a][b][m][n] = (f32x4){0.f, 0.f, 0.f, 0.f};
;     bf16x8 At[4][2], B0[2][2], B1[2][2];
;     const char* cA = (const char*)g.asel(cur.pn) + (size_t)cur.pm * tstep; const char* cB = (const char*)g.Bt + (size_t)cur.pn * tstep;
;     S.a_ready(cur);
;     if constexpr (SP2) {
;         PG8_STAGE(PG8_SB(0, 0), cB, voffB); PG8_STAGE(PG8_SB(0, 1), cB + hstep, voffB); PG8_STAGE(PG8_SA(0, 0), cA, voffA); PG8_STAGE(PG8_SA(0, 1), cA + hstep, voffA);
;         if (wr == 1) PG8_BAR;
.LBB0_725:
	v_readlane_b32 s2, v254, 1
	v_readlane_b32 s3, v254, 2
	s_cmp_lt_i32 s2, 9
	s_cselect_b64 s[2:3], -1, 0
	s_and_b64 s[8:9], s[2:3], s[0:1]
	s_andn2_b64 vcc, exec, s[8:9]
	s_cbranch_vccnz .LBB0_746
	v_readlane_b32 s98, v254, 3
	s_cmp_ge_u32 s98, 0x100
	s_cbranch_scc0 .Lmy_prio_8
	s_setprio 1
.Lmy_prio_8:
	v_mbcnt_lo_u32_b32 v8, -1, 0
	v_mbcnt_hi_u32_b32 v8, -1, v8
	s_cmpk_gt_i32 s84, 0x3ff
	v_add_u32_e32 v0, s52, v8
	s_mov_b64 s[0:1], s[82:83]
	v_readfirstlane_b32 s2, v0
	s_cbranch_scc1 .LBB0_746
	v_lshlrev_b32_e32 v1, 4, v0
	v_add_u32_e32 v2, 0x2000, v1
	v_ashrrev_i32_e32 v3, 31, v2
	v_lshrrev_b32_e32 v3, 22, v3
	v_add_u32_e32 v3, v2, v3
	v_ashrrev_i32_e32 v9, 10, v3
	v_mul_i32_i24_e32 v3, 0x400, v9
	v_sub_u32_e32 v2, v2, v3
	v_lshrrev_b32_e32 v3, 4, v2
	v_bitop3_b32 v2, v3, v2, 32 bitop3:0x6c
	v_ashrrev_i32_e32 v3, 31, v2
	v_lshrrev_b32_e32 v3, 26, v3
	v_add_u32_e32 v3, v2, v3
	v_lshlrev_b32_e32 v4, 3, v9
	v_ashrrev_i32_e32 v10, 6, v3
	v_and_b32_e32 v4, -16, v4
	v_add_u32_e32 v4, v10, v4
	s_load_dwordx4 s[4:7], s[0:1], 0xc0
	v_and_b32_e32 v5, 3, v10
	s_mov_b32 s0, 0x1fffe0
	v_lshrrev_b32_e32 v6, 2, v4
	v_lshlrev_b32_e32 v7, 1, v4
	v_and_b32_e32 v3, 0xc0, v3
	v_and_or_b32 v5, v4, s0, v5
	v_and_b32_e32 v6, 4, v6
	v_and_b32_e32 v7, 24, v7
	v_sub_u32_e32 v2, v2, v3
	v_mov_b32_e32 v3, 1
	v_or3_b32 v5, v5, v6, v7
	v_lshlrev_b32_e32 v6, 5, v9
	v_ashrrev_i16_sdwa v2, v3, sext(v2) dst_sel:DWORD dst_unused:UNUSED_PAD src0_sel:DWORD src1_sel:BYTE_0
	v_and_b32_e32 v6, 32, v6
	v_bfe_i32 v11, v2, 0, 16
	v_add_lshl_u32 v2, v6, v11, 1
	v_lshl_add_u32 v128, v5, 11, v2
	v_lshl_add_u32 v130, v4, 11, v2
	v_bfe_i32 v2, v0, 27, 1
	v_lshrrev_b32_e32 v2, 22, v2
	v_add_u32_e32 v2, v1, v2
	v_and_b32_e32 v2, 0xfffffc00, v2
	v_sub_u32_e32 v1, v1, v2
	v_lshrrev_b32_e32 v2, 4, v1
	v_ashrrev_i32_e32 v4, 31, v0
	s_waitcnt lgkmcnt(0)
	s_add_u32 s33, s6, 0x8000000
	v_bitop3_b32 v1, v2, v1, 32 bitop3:0x6c
	v_lshrrev_b32_e32 v4, 26, v4
	s_addc_u32 s36, s7, 0
	v_ashrrev_i32_e32 v2, 31, v1
	v_add_u32_e32 v0, v0, v4
	s_add_u32 s37, s6, 0x1100000
	v_lshrrev_b32_e32 v2, 26, v2
	v_ashrrev_i32_e32 v13, 6, v0
	s_addc_u32 s38, s7, 0
	v_add_u32_e32 v2, v1, v2
	v_lshlrev_b32_e32 v0, 3, v13
	s_add_u32 s39, s6, 0xc000000
	v_ashrrev_i32_e32 v12, 6, v2
	v_and_b32_e32 v0, -16, v0
	s_addc_u32 s40, s7, 0
	v_add_u32_e32 v0, v12, v0
	v_and_b32_e32 v4, 3, v12
	s_ashr_i32 s42, s84, 31
	v_and_or_b32 v4, v0, s0, v4
	s_lshr_b32 s0, s42, 29
	s_add_i32 s0, s84, s0
	s_and_b32 s1, s0, -8
	s_ashr_i32 s14, s2, 6
	s_sub_i32 s1, s84, s1
	s_ashr_i32 s3, s2, 8
	s_lshl_b32 s41, s14, 10
	s_lshl_b32 s11, s1, 7
	s_ashr_i32 s0, s0, 3
	s_mul_i32 s10, s1, 0x81
	s_cmp_lt_i32 s1, 0
	s_cselect_b32 s1, s10, s11
	s_add_i32 s1, s1, s0
	s_mul_hi_i32 s0, s1, 0x2aaaaaab
	s_lshr_b32 s10, s0, 31
	s_ashr_i32 s0, s0, 3
	v_lshrrev_b32_e32 v5, 2, v0
	v_lshlrev_b32_e32 v6, 1, v0
	v_and_b32_e32 v2, 0xc0, v2
	s_add_i32 s0, s0, s10
	v_and_b32_e32 v5, 4, v5
	v_and_b32_e32 v6, 24, v6
	v_sub_u32_e32 v1, v1, v2
	s_mul_i32 s10, s0, 6
	v_or3_b32 v4, v4, v5, v6
	v_lshlrev_b32_e32 v5, 5, v13
	v_ashrrev_i16_sdwa v1, v3, sext(v1) dst_sel:DWORD dst_unused:UNUSED_PAD src0_sel:DWORD src1_sel:BYTE_0
	s_sub_i32 s11, 0x80, s10
	s_mul_i32 s0, s0, 48
	v_and_b32_e32 v5, 32, v5
	v_bfe_i32 v14, v1, 0, 16
	s_min_u32 s11, s11, 6
	s_sub_i32 s12, s1, s0
	v_add_lshl_u32 v1, v5, v14, 1
	s_sext_i32_i8 s0, s12
	v_cvt_f32_ubyte0_e32 v3, s11
	v_lshl_add_u32 v132, v4, 11, v1
	v_cvt_f32_i32_e32 v2, s0
	v_rcp_iflag_f32_e32 v4, v3
	v_lshl_add_u32 v134, v0, 11, v1
	s_ashr_i32 s0, s0, 30
	s_or_b32 s13, s0, 1
	v_mul_f32_e32 v0, v2, v4
	v_trunc_f32_e32 v0, v0
	v_fma_f32 v1, -v0, v3, v2
	v_cvt_i32_f32_e32 v0, v0
	v_cmp_ge_f32_e64 s[0:1], |v1|, v3
	s_and_b64 s[0:1], s[0:1], exec
	s_cselect_b32 s0, s13, 0
	v_readfirstlane_b32 s1, v0
	s_add_i32 s0, s1, s0
	s_mul_i32 s11, s0, s11
	s_sub_i32 s11, s12, s11
	s_sext_i32_i8 s11, s11
	s_bfe_i32 s1, s0, 0x80000
	s_add_i32 s28, s10, s11
	s_sext_i32_i16 s63, s1
	s_ashr_i32 s29, s28, 31
	s_bfe_i64 s[0:1], s[0:1], 0x80000
	s_lshl_b64 s[10:11], s[28:29], 19
	s_lshl_b64 s[0:1], s[0:1], 19
	s_add_u32 s30, s37, s0
	s_addc_u32 s31, s38, s1
	s_add_i32 s29, s41, 0
	s_add_i32 m0, s29, 0x10000
	s_add_i32 s0, s29, 0x12000
	s_cmp_lt_i32 s63, 4
	global_load_lds_dwordx4 v132, s[30:31]
	s_mov_b32 m0, s0
	s_cselect_b32 s12, s36, s40
	s_cselect_b32 s13, s33, s39
	s_add_u32 s0, s30, 0x40000
	global_load_lds_dwordx4 v128, s[30:31]
	s_addc_u32 s1, s31, 0
	s_add_i32 m0, s29, 0x14000
	v_mov_b32_e32 v133, 0
	global_load_lds_dwordx4 v132, s[0:1]
	s_add_i32 m0, s29, 0x16000
	v_mov_b32_e32 v129, v133
	global_load_lds_dwordx4 v128, s[0:1]
	s_add_u32 s0, s13, s10
	s_addc_u32 s1, s12, s11
	s_add_i32 s43, s29, 0x2000
	s_mov_b32 m0, s29
	s_add_u32 s10, s0, 0x40000
	global_load_lds_dwordx4 v134, s[0:1]
	s_mov_b32 m0, s43
	s_addc_u32 s11, s1, 0
	s_add_i32 s44, s29, 0x4000
	global_load_lds_dwordx4 v130, s[0:1]
	s_mov_b32 m0, s44
	s_add_i32 s45, s29, 0x6000
	global_load_lds_dwordx4 v134, s[10:11]
	s_mov_b32 m0, s45
	v_mov_b32_e32 v135, v133
	global_load_lds_dwordx4 v130, s[10:11]
	v_mov_b32_e32 v131, v133
	s_cmp_eq_u32 s3, 1
	s_mov_b32 s46, 0
	v_lshl_add_u64 v[6:7], s[30:31], 0, v[132:133]
	v_lshl_add_u64 v[2:3], s[30:31], 0, v[128:129]
	s_mov_b64 s[10:11], 0x40000
	v_lshl_add_u64 v[0:1], s[0:1], 0, v[134:135]
	s_cselect_b64 s[12:13], -1, 0
	s_cmp_lg_u32 s3, 1
	v_lshl_add_u64 v[4:5], s[0:1], 0, v[130:131]
	s_cbranch_scc1 .LBB0_729
	s_barrier

; __device__ __forceinline__ unsigned xb_ld(unsigned* p)              { return __hip_atomic_load(p, __ATOMIC_RELAXED, __HIP_MEMORY_SCOPE_AGENT); }
; __device__ __forceinline__ unsigned xb_add(unsigned* p, unsigned v) { return __hip_atomic_fetch_add(p, v, __ATOMIC_RELAXED, __HIP_MEMORY_SCOPE_AGENT); }
; __device__ __forceinline__ void xcd_barrier_complete(unsigned* bar, unsigned x, unsigned& nloc, unsigned& nx) {
;     const unsigned G = gridDim.x * gridDim.y * gridDim.z;
;     unsigned sum, cnt, mine, sp = 0u;
;     for (;;) {
;         sum = 0u; cnt = 0u; mine = 0u;
; #pragma unroll
;         for (unsigned j = 0; j < 16; ++j) { const unsigned c = xb_ld(&bar[XB_XCNT(j)]); sum += c; cnt += (c > 0u) ? 1u : 0u; mine = (j == x) ? c : mine; }
; __device__ __forceinline__ void xcd_barrier(const XcdBarrier& b, const int tid_) {
;     asm volatile("s_waitcnt vmcnt(0)" ::: "memory");
;     __syncthreads();
;     if (tid_ == 0) {
;         unsigned* bar = b.bar;
;         __builtin_amdgcn_s_waitcnt(0);
;         unsigned nloc = b.st[0], nx = b.st[1];
;         if (nloc == 0u) { xcd_barrier_complete(bar, b.x, nloc, nx); b.st[0] = nloc; b.st[1] = nx; }
;         const unsigned old = xb_add(&bar[XB_XSUB(b.x)], 1u);
.LBB0_746:
	s_setprio 0
	v_readlane_b32 s0, v254, 1
	v_readlane_b32 s1, v254, 2
	s_cmp_gt_i32 s1, 9
	s_cselect_b64 s[0:1], -1, 0
	s_and_b64 s[2:3], s[8:9], s[0:1]
	s_andn2_b64 vcc, exec, s[2:3]
	s_cbranch_vccnz .LBB0_800
	s_mov_b64 s[4:5], s[82:83]
	v_mbcnt_lo_u32_b32 v0, -1, 0
	v_mbcnt_hi_u32_b32 v0, -1, v0
	s_getreg_b32 s6, hwreg(HW_REG_XCC_ID, 0, 4)
	s_waitcnt vmcnt(0)
	v_sub_u32_e32 v0, 0, v0
	v_cmp_eq_u32_e32 vcc, s52, v0
	s_waitcnt vmcnt(0)
	s_barrier
	s_and_saveexec_b64 s[2:3], vcc
	s_cbranch_execz .LBB0_799
	s_add_i32 s7, 0, 0x23fc0
	v_mov_b32_e32 v0, s7
	s_load_dwordx2 s[4:5], s[4:5], 0xc8
	s_waitcnt vmcnt(0) expcnt(0) lgkmcnt(0)
	ds_read_b32 v2, v0
	s_add_i32 s7, 0, 0x23fc4
	v_mov_b32_e32 v0, s7
	ds_read_b32 v0, v0
	s_and_b32 s33, s6, 15
	s_waitcnt lgkmcnt(1)
	v_cmp_ne_u32_e32 vcc, 0, v2
	s_cbranch_vccnz .LBB0_763
	s_load_dword s6, s[82:83], 0xe0
	s_mov_b32 s49, 1
	v_mov_b32_e32 v16, 0
	s_waitcnt lgkmcnt(0)
	s_mul_i32 s48, s55, s6
	s_add_u32 s6, s4, 0x1900200
	s_addc_u32 s7, s5, 0
	s_add_u32 s8, s4, 0x1900400
	s_addc_u32 s9, s5, 0
	s_add_u32 s10, s4, 0x1900500
	s_addc_u32 s11, s5, 0
	s_add_u32 s12, s4, 0x1900600
	s_addc_u32 s13, s5, 0
	s_add_u32 s14, s4, 0x1900700
	s_addc_u32 s15, s5, 0
	s_add_u32 s16, s4, 0x1900800
	s_addc_u32 s17, s5, 0
	s_add_u32 s18, s4, 0x1900900
	s_addc_u32 s19, s5, 0
	s_add_u32 s20, s4, 0x1900a00
	s_addc_u32 s21, s5, 0
	s_add_u32 s22, s4, 0x1900b00
	s_addc_u32 s23, s5, 0
	s_add_u32 s24, s4, 0x1900c00
	s_addc_u32 s25, s5, 0
	s_add_u32 s26, s4, 0x1900d00
	s_addc_u32 s27, s5, 0
	s_add_u32 s28, s4, 0x1900e00
	s_addc_u32 s29, s5, 0
	s_add_u32 s30, s4, 0x1900f00
	s_addc_u32 s31, s5, 0
	s_add_u32 s34, s4, 0x1901000
	s_addc_u32 s35, s5, 0
	s_add_u32 s36, s4, 0x1901100
	s_addc_u32 s37, s5, 0
	s_add_u32 s38, s4, 0x1901200
	s_addc_u32 s39, s5, 0
	s_add_u32 s40, s4, 0x1901300
	s_mul_i32 s48, s48, s54
	s_addc_u32 s41, s5, 0
	s_branch .LBB0_751

; #define PG8_BAR __builtin_amdgcn_s_barrier()
;     __host__ __device__ bool next(int i, Unit& u) const {
;         const long L = (long)i * G + c; if (L >= nwg) return false;
;         int wgid = (int)L; { const int q = nwg / NXCD, r = nwg % NXCD, xcd = wgid % NXCD, off = wgid / NXCD; wgid = (xcd < r ? xcd * (q + 1) : r * (q + 1) + (xcd - r) * q) + off; }
;         const int nig = wgm * nN, gid = wgid / nig, fm = gid * wgm, gsz = (nM - fm) < wgm ? (nM - fm) : wgm;
;         u.pm = fm + ((wgid % nig) % gsz); u.pn = (wgid % nig) / gsz; return true;
; template <class Epi, class Sched, bool ALIGN_EPI = false, bool SP2 = false>
; __device__ __forceinline__ void gemm_phase(PG8_LAS unsigned char* lds, const Gemm g, const Sched& S, const Epi& E, const int tid_in) {
;     const int tid = tid_in, wid = __builtin_amdgcn_readfirstlane(tid >> 6), lane = tid & 63, wr = wid >> 2, wc = wid & 3, fr = lane & 15, fq = lane >> 4;
;     const int K = g.K, nt = K / BK;
;     unsigned voffA[2], voffB[2];
; #pragma unroll
;     for (int i = 0; i < 2; ++i) { int R, C; stage_rc(tid * 16 + i * 8192, R, C); const int Rb = Epi::PERM ? ((R & ~31) + perm32(R & 31)) : R;
;         voffA[i] = (unsigned)(R * K + C) * 2u; voffB[i] = (unsigned)(Rb * K + C) * 2u; }
;     const size_t kstep = (size_t)(BK * 2);
;     const size_t hstep = (size_t)HALF * K * 2;
;     const size_t tstep = 2 * hstep;
;     const unsigned ldsw = (unsigned)wid * 1024u;
;     const int aoff = lds_byte(wr * 64 + fr, fq * 8), boff = lds_byte(wc * 32 + fr, fq * 8);
;     ...
;     Unit cur, nxt; int ui = 0;
;     if (!S.next(0, cur)) return;
;     f32x4 acc[2][2][4][2];
; #pragma unroll
;     for (int a = 0; a < 2; ++a)
; #pragma unroll
;         for (int b = 0; b < 2; ++b)
; #pragma unroll
;             for (int m = 0; m < 4; ++m)
; #pragma unroll
;                 for (int n = 0; n < 2; ++n) acc[a][b][m][n] = (f32x4){0.f, 0.f, 0.f, 0.f};
;     bf16x8 At[4][2], B0[2][2], B1[2][2];
;     const char* cA = (const char*)g.asel(cur.pn) + (size_t)cur.pm * tstep; const char* cB = (const char*)g.Bt + (size_t)cur.pn * tstep;
;     S.a_ready(cur);
;     if constexpr (SP2) {
;         PG8_STAGE(PG8_SB(0, 0), cB, voffB); PG8_STAGE(PG8_SB(0, 1), cB + hstep, voffB); PG8_STAGE(PG8_SA(0, 0), cA, voffA); PG8_STAGE(PG8_SA(0, 1), cA + hstep, voffA);
;         if (wr == 1) PG8_BAR;
.LBB0_800:
	v_readlane_b32 s2, v254, 1
	v_readlane_b32 s3, v254, 2
	s_cmp_lt_i32 s2, 10
	s_cselect_b64 s[2:3], -1, 0
	s_and_b64 s[4:5], s[2:3], s[0:1]
	s_andn2_b64 vcc, exec, s[4:5]
	s_cbranch_vccnz .LBB0_819
	v_readlane_b32 s98, v254, 3
	s_cmp_ge_u32 s98, 0x100
	s_cbranch_scc0 .Lmy_prio_9
	s_setprio 1
.Lmy_prio_9:
	v_mbcnt_lo_u32_b32 v8, -1, 0
	v_mbcnt_hi_u32_b32 v8, -1, v8
	s_cmpk_gt_i32 s84, 0x3ff
	v_add_u32_e32 v0, s52, v8
	s_mov_b64 s[8:9], s[82:83]
	v_readfirstlane_b32 s17, v0
	s_cbranch_scc1 .LBB0_819
	v_lshlrev_b32_e32 v1, 4, v0
	v_add_u32_e32 v2, 0x2000, v1
	v_ashrrev_i32_e32 v3, 31, v2
	v_lshrrev_b32_e32 v3, 22, v3
	v_add_u32_e32 v3, v2, v3
	v_ashrrev_i32_e32 v3, 10, v3
	v_mul_i32_i24_e32 v4, 0x400, v3
	v_sub_u32_e32 v2, v2, v4
	v_lshrrev_b32_e32 v4, 4, v2
	v_bitop3_b32 v2, v4, v2, 32 bitop3:0x6c
	v_ashrrev_i32_e32 v4, 31, v2
	v_lshrrev_b32_e32 v4, 26, v4
	v_add_u32_e32 v4, v2, v4
	v_lshlrev_b32_e32 v6, 3, v3
	v_ashrrev_i32_e32 v5, 6, v4
	v_and_b32_e32 v6, -16, v6
	v_and_b32_e32 v4, 0xc0, v4
	v_add_u32_e32 v6, v5, v6
	v_sub_u32_e32 v2, v2, v4
	v_mov_b32_e32 v4, 1
	v_and_b32_e32 v5, 3, v5
	s_mov_b32 s0, 0xffffe0
	v_lshrrev_b32_e32 v7, 2, v6
	v_lshlrev_b32_e32 v9, 1, v6
	v_lshlrev_b32_e32 v3, 5, v3
	v_ashrrev_i16_sdwa v2, v4, sext(v2) dst_sel:DWORD dst_unused:UNUSED_PAD src0_sel:DWORD src1_sel:BYTE_0
	v_and_or_b32 v5, v6, s0, v5
	v_and_b32_e32 v7, 4, v7
	v_and_b32_e32 v9, 24, v9
	v_and_b32_e32 v3, 32, v3
	v_bfe_i32 v2, v2, 0, 16
	v_or3_b32 v5, v5, v7, v9
	v_add_lshl_u32 v2, v3, v2, 1
	v_lshl_add_u32 v128, v5, 8, v2
	v_lshl_add_u32 v130, v6, 8, v2
	v_bfe_i32 v2, v0, 27, 1
	v_lshrrev_b32_e32 v2, 22, v2
	v_add_u32_e32 v2, v1, v2
	v_and_b32_e32 v2, 0xfffffc00, v2
	s_load_dwordx2 s[2:3], s[8:9], 0xc8
	s_load_dwordx2 s[6:7], s[8:9], 0x60
	v_sub_u32_e32 v1, v1, v2
	v_lshrrev_b32_e32 v2, 4, v1
	v_ashrrev_i32_e32 v5, 31, v0
	v_bitop3_b32 v1, v2, v1, 32 bitop3:0x6c
	v_lshrrev_b32_e32 v5, 26, v5
	v_ashrrev_i32_e32 v2, 31, v1
	v_add_u32_e32 v0, v0, v5
	s_waitcnt lgkmcnt(0)
	s_add_u32 s33, s2, 0x10000000
	v_lshrrev_b32_e32 v2, 26, v2
	v_ashrrev_i32_e32 v0, 6, v0
	s_addc_u32 s46, s3, 0
	v_add_u32_e32 v2, v1, v2
	v_lshlrev_b32_e32 v5, 3, v0
	s_add_u32 s47, s2, 0x1680000
	v_ashrrev_i32_e32 v3, 6, v2
	v_and_b32_e32 v5, -16, v5
	s_addc_u32 s48, s3, 0
	v_add_u32_e32 v5, v3, v5
	v_and_b32_e32 v3, 3, v3
	s_ashr_i32 s19, s84, 31
	v_and_or_b32 v3, v5, s0, v3
	s_lshr_b32 s0, s19, 29
	s_add_i32 s0, s84, s0
	s_and_b32 s1, s0, -8
	s_ashr_i32 s14, s17, 6
	s_sub_i32 s1, s84, s1
	s_ashr_i32 s18, s17, 8
	s_lshl_b32 s49, s14, 10
	s_lshl_b32 s11, s1, 7
	s_ashr_i32 s0, s0, 3
	s_mul_i32 s10, s1, 0x81
	s_cmp_lt_i32 s1, 0
	s_cselect_b32 s1, s10, s11
	s_add_i32 s1, s1, s0
	s_mul_hi_i32 s0, s1, 0x2aaaaaab
	s_lshr_b32 s10, s0, 31
	s_ashr_i32 s0, s0, 4
	v_and_b32_e32 v2, 0xc0, v2
	s_add_i32 s0, s0, s10
	v_sub_u32_e32 v1, v1, v2
	s_mul_i32 s10, s0, 12
	v_lshrrev_b32_e32 v6, 2, v5
	v_lshlrev_b32_e32 v7, 1, v5
	v_lshlrev_b32_e32 v0, 5, v0
	v_ashrrev_i16_sdwa v1, v4, sext(v1) dst_sel:DWORD dst_unused:UNUSED_PAD src0_sel:DWORD src1_sel:BYTE_0
	s_sub_i32 s11, 0x80, s10
	s_mulk_i32 s0, 0x60
	v_and_b32_e32 v6, 4, v6
	v_and_b32_e32 v7, 24, v7
	v_and_b32_e32 v0, 32, v0
	v_bfe_i32 v1, v1, 0, 16
	s_min_u32 s11, s11, 12
	s_sub_i32 s12, s1, s0
	v_or3_b32 v3, v3, v6, v7
	v_add_lshl_u32 v0, v0, v1, 1
	s_sext_i32_i8 s0, s12
	v_cvt_f32_ubyte0_e32 v2, s11
	v_lshl_add_u32 v132, v3, 8, v0
	v_cvt_f32_i32_e32 v1, s0
	v_rcp_iflag_f32_e32 v3, v2
	v_lshl_add_u32 v134, v5, 8, v0
	s_ashr_i32 s0, s0, 30
	s_or_b32 s13, s0, 1
	v_mul_f32_e32 v0, v1, v3
	v_trunc_f32_e32 v0, v0
	v_fma_f32 v1, -v0, v2, v1
	v_cvt_i32_f32_e32 v0, v0
	v_cmp_ge_f32_e64 s[0:1], |v1|, v2
	s_and_b64 s[0:1], s[0:1], exec
	s_cselect_b32 s0, s13, 0
	v_readfirstlane_b32 s1, v0
	s_add_i32 s16, s1, s0
	s_mul_i32 s0, s16, s11
	s_sub_i32 s0, s12, s0
	s_sext_i32_i8 s0, s0
	s_add_i32 s0, s10, s0
	s_ashr_i32 s1, s0, 31
	s_bfe_i64 s[12:13], s[16:17], 0x80000
	s_lshl_b64 s[10:11], s[0:1], 16
	s_lshl_b64 s[12:13], s[12:13], 16
	s_add_u32 s40, s47, s12
	s_addc_u32 s41, s48, s13
	s_add_i32 s50, s49, 0
	s_add_i32 m0, s50, 0x10000
	s_load_dwordx2 s[8:9], s[8:9], 0x48
	global_load_lds_dwordx4 v132, s[40:41]
	s_add_i32 m0, s50, 0x12000
	s_add_u32 s12, s40, 0x8000
	global_load_lds_dwordx4 v128, s[40:41]
	s_addc_u32 s13, s41, 0
	s_add_i32 m0, s50, 0x14000
	v_mov_b32_e32 v137, 0
	global_load_lds_dwordx4 v132, s[12:13]
	s_add_i32 m0, s50, 0x16000
	s_add_u32 s42, s33, s10
	s_addc_u32 s43, s46, s11
	s_add_i32 s51, s50, 0x2000
	global_load_lds_dwordx4 v128, s[12:13]
	s_mov_b32 m0, s50
	s_add_u32 s10, s42, 0x8000
	global_load_lds_dwordx4 v134, s[42:43]
	s_mov_b32 m0, s51
	s_addc_u32 s11, s43, 0
	s_add_i32 s52, s50, 0x4000
	global_load_lds_dwordx4 v130, s[42:43]
	s_mov_b32 m0, s52
	s_add_i32 s53, s50, 0x6000
	global_load_lds_dwordx4 v134, s[10:11]
	s_mov_b32 m0, s53
	v_mov_b32_e32 v133, v137
	global_load_lds_dwordx4 v130, s[10:11]
	v_mov_b32_e32 v129, v137
	v_mov_b32_e32 v135, v137
	v_mov_b32_e32 v131, v137
	s_cmp_eq_u32 s18, 1
	v_lshl_add_u64 v[6:7], s[40:41], 0, v[132:133]
	v_lshl_add_u64 v[4:5], s[40:41], 0, v[128:129]
	v_lshl_add_u64 v[0:1], s[42:43], 0, v[134:135]
	s_cselect_b64 s[10:11], -1, 0
	s_cmp_lg_u32 s18, 1
	v_lshl_add_u64 v[2:3], s[42:43], 0, v[130:131]
	s_cbranch_scc1 .LBB0_804
	s_barrier

; __device__ __forceinline__ unsigned xb_ld(unsigned* p)              { return __hip_atomic_load(p, __ATOMIC_RELAXED, __HIP_MEMORY_SCOPE_AGENT); }
; __device__ __forceinline__ unsigned xb_add(unsigned* p, unsigned v) { return __hip_atomic_fetch_add(p, v, __ATOMIC_RELAXED, __HIP_MEMORY_SCOPE_AGENT); }
; __device__ __forceinline__ void xcd_barrier_complete(unsigned* bar, unsigned x, unsigned& nloc, unsigned& nx) {
;     const unsigned G = gridDim.x * gridDim.y * gridDim.z;
;     unsigned sum, cnt, mine, sp = 0u;
;     for (;;) {
;         sum = 0u; cnt = 0u; mine = 0u;
; #pragma unroll
;         for (unsigned j = 0; j < 16; ++j) { const unsigned c = xb_ld(&bar[XB_XCNT(j)]); sum += c; cnt += (c > 0u) ? 1u : 0u; mine = (j == x) ? c : mine; }
; __device__ __forceinline__ void xcd_barrier(const XcdBarrier& b, const int tid_) {
;     asm volatile("s_waitcnt vmcnt(0)" ::: "memory");
;     __syncthreads();
;     if (tid_ == 0) {
;         unsigned* bar = b.bar;
;         __builtin_amdgcn_s_waitcnt(0);
;         unsigned nloc = b.st[0], nx = b.st[1];
;         if (nloc == 0u) { xcd_barrier_complete(bar, b.x, nloc, nx); b.st[0] = nloc; b.st[1] = nx; }
;         const unsigned old = xb_add(&bar[XB_XSUB(b.x)], 1u);
.LBB0_819:
	s_setprio 0
	v_readlane_b32 s0, v254, 1
	v_readlane_b32 s1, v254, 2
	s_cmp_gt_i32 s1, 10
	s_cselect_b64 s[0:1], -1, 0
	s_and_b64 s[2:3], s[4:5], s[0:1]
	s_andn2_b64 vcc, exec, s[2:3]
	s_cbranch_vccnz .LBB0_873
	s_mov_b64 s[4:5], s[82:83]
	v_mbcnt_lo_u32_b32 v0, -1, 0
	v_mbcnt_hi_u32_b32 v0, -1, v0
	s_getreg_b32 s6, hwreg(HW_REG_XCC_ID, 0, 4)
	s_waitcnt vmcnt(0)
	v_sub_u32_e32 v0, 0, v0
	v_cmp_eq_u32_e32 vcc, s52, v0
	s_waitcnt vmcnt(0)
	s_barrier
	s_and_saveexec_b64 s[2:3], vcc
	s_cbranch_execz .LBB0_872
	s_add_i32 s7, 0, 0x23fc0
	v_mov_b32_e32 v0, s7
	s_load_dwordx2 s[4:5], s[4:5], 0xc8
	s_waitcnt vmcnt(0) expcnt(0) lgkmcnt(0)
	ds_read_b32 v2, v0
	s_add_i32 s7, 0, 0x23fc4
	v_mov_b32_e32 v0, s7
	ds_read_b32 v0, v0
	s_and_b32 s33, s6, 15
	s_waitcnt lgkmcnt(1)
	v_cmp_ne_u32_e32 vcc, 0, v2
	s_cbranch_vccnz .LBB0_836
	s_load_dword s6, s[82:83], 0xe0
	s_mov_b32 s49, 1
	v_mov_b32_e32 v16, 0
	s_waitcnt lgkmcnt(0)
	s_mul_i32 s48, s55, s6
	s_add_u32 s6, s4, 0x1900200
	s_addc_u32 s7, s5, 0
	s_add_u32 s8, s4, 0x1900400
	s_addc_u32 s9, s5, 0
	s_add_u32 s10, s4, 0x1900500
	s_addc_u32 s11, s5, 0
	s_add_u32 s12, s4, 0x1900600
	s_addc_u32 s13, s5, 0
	s_add_u32 s14, s4, 0x1900700
	s_addc_u32 s15, s5, 0
	s_add_u32 s16, s4, 0x1900800
	s_addc_u32 s17, s5, 0
	s_add_u32 s18, s4, 0x1900900
	s_addc_u32 s19, s5, 0
	s_add_u32 s20, s4, 0x1900a00
	s_addc_u32 s21, s5, 0
	s_add_u32 s22, s4, 0x1900b00
	s_addc_u32 s23, s5, 0
	s_add_u32 s24, s4, 0x1900c00
	s_addc_u32 s25, s5, 0
	s_add_u32 s26, s4, 0x1900d00
	s_addc_u32 s27, s5, 0
	s_add_u32 s28, s4, 0x1900e00
	s_addc_u32 s29, s5, 0
	s_add_u32 s30, s4, 0x1900f00
	s_addc_u32 s31, s5, 0
	s_add_u32 s34, s4, 0x1901000
	s_addc_u32 s35, s5, 0
	s_add_u32 s36, s4, 0x1901100
	s_addc_u32 s37, s5, 0
	s_add_u32 s38, s4, 0x1901200
	s_addc_u32 s39, s5, 0
	s_add_u32 s40, s4, 0x1901300
	s_mul_i32 s48, s48, s54
	s_addc_u32 s41, s5, 0
	s_branch .LBB0_824

; #define PG8_BAR __builtin_amdgcn_s_barrier()
;     __host__ __device__ bool next(int i, Unit& u) const {
;         const long L = (long)i * G + c; if (L >= nwg) return false;
;         int wgid = (int)L; { const int q = nwg / NXCD, r = nwg % NXCD, xcd = wgid % NXCD, off = wgid / NXCD; wgid = (xcd < r ? xcd * (q + 1) : r * (q + 1) + (xcd - r) * q) + off; }
;         const int nig = wgm * nN, gid = wgid / nig, fm = gid * wgm, gsz = (nM - fm) < wgm ? (nM - fm) : wgm;
;         u.pm = fm + ((wgid % nig) % gsz); u.pn = (wgid % nig) / gsz; return true;
; template <class Epi, class Sched, bool ALIGN_EPI = false, bool SP2 = false>
; __device__ __forceinline__ void gemm_phase(PG8_LAS unsigned char* lds, const Gemm g, const Sched& S, const Epi& E, const int tid_in) {
;     const int tid = tid_in, wid = __builtin_amdgcn_readfirstlane(tid >> 6), lane = tid & 63, wr = wid >> 2, wc = wid & 3, fr = lane & 15, fq = lane >> 4;
;     const int K = g.K, nt = K / BK;
;     unsigned voffA[2], voffB[2];
; #pragma unroll
;     for (int i = 0; i < 2; ++i) { int R, C; stage_rc(tid * 16 + i * 8192, R, C); const int Rb = Epi::PERM ? ((R & ~31) + perm32(R & 31)) : R;
;         voffA[i] = (unsigned)(R * K + C) * 2u; voffB[i] = (unsigned)(Rb * K + C) * 2u; }
;     const size_t kstep = (size_t)(BK * 2);
;     const size_t hstep = (size_t)HALF * K * 2;
;     const size_t tstep = 2 * hstep;
;     const unsigned ldsw = (unsigned)wid * 1024u;
;     const int aoff = lds_byte(wr * 64 + fr, fq * 8), boff = lds_byte(wc * 32 + fr, fq * 8);
;     ...
;     Unit cur, nxt; int ui = 0;
;     if (!S.next(0, cur)) return;
;     f32x4 acc[2][2][4][2];
; #pragma unroll
;     for (int a = 0; a < 2; ++a)
; #pragma unroll
;         for (int b = 0; b < 2; ++b)
; #pragma unroll
;             for (int m = 0; m < 4; ++m)
; #pragma unroll
;                 for (int n = 0; n < 2; ++n) acc[a][b][m][n] = (f32x4){0.f, 0.f, 0.f, 0.f};
;     bf16x8 At[4][2], B0[2][2], B1[2][2];
;     const char* cA = (const char*)g.asel(cur.pn) + (size_t)cur.pm * tstep; const char* cB = (const char*)g.Bt + (size_t)cur.pn * tstep;
;     S.a_ready(cur);
;     if constexpr (SP2) {
;         PG8_STAGE(PG8_SB(0, 0), cB, voffB); PG8_STAGE(PG8_SB(0, 1), cB + hstep, voffB); PG8_STAGE(PG8_SA(0, 0), cA, voffA); PG8_STAGE(PG8_SA(0, 1), cA + hstep, voffA);
;         if (wr == 1) PG8_BAR;
.LBB0_1066:
	v_readlane_b32 s2, v254, 1
	v_readlane_b32 s3, v254, 2
	s_cmp_lt_i32 s2, 13
	s_cselect_b64 s[2:3], -1, 0
	s_and_b64 s[4:5], s[2:3], s[0:1]
	s_andn2_b64 vcc, exec, s[4:5]
	s_cbranch_vccnz .LBB0_1107
	v_readlane_b32 s98, v254, 3
	s_cmp_ge_u32 s98, 0x100
	s_cbranch_scc0 .Lmy_prio_12
	s_setprio 1
.Lmy_prio_12:
	v_mbcnt_lo_u32_b32 v0, -1, 0
	v_mbcnt_hi_u32_b32 v0, -1, v0
	s_cmpk_lt_i32 s84, 0x200
	v_add_u32_e32 v155, s52, v0
	v_ashrrev_i32_e32 v2, 31, v155
	v_lshrrev_b32_e32 v2, 26, v2
	v_add_u32_e32 v2, v155, v2
	v_ashrrev_i32_e32 v8, 6, v2
	v_bfe_i32 v2, v155, 27, 1
	v_lshlrev_b32_e32 v1, 4, v155
	v_lshrrev_b32_e32 v2, 22, v2
	v_add_u32_e32 v2, v1, v2
	v_and_b32_e32 v2, 0xfffffc00, v2
	v_sub_u32_e32 v2, v1, v2
	v_lshrrev_b32_e32 v3, 4, v2
	v_bitop3_b32 v2, v3, v2, 32 bitop3:0x6c
	v_ashrrev_i32_e32 v4, 31, v2
	v_lshrrev_b32_e32 v4, 26, v4
	v_add_u32_e32 v4, v2, v4
	v_lshlrev_b32_e32 v3, 3, v8
	v_ashrrev_i32_e32 v9, 6, v4
	v_and_b32_e32 v4, 0xc0, v4
	v_and_b32_e32 v3, -16, v3
	v_sub_u32_e32 v2, v2, v4
	v_mov_b32_e32 v4, 1
	v_add_u32_e32 v154, v9, v3
	v_lshlrev_b32_e32 v3, 5, v8
	v_ashrrev_i16_sdwa v2, v4, sext(v2) dst_sel:DWORD dst_unused:UNUSED_PAD src0_sel:DWORD src1_sel:BYTE_0
	v_and_b32_e32 v3, 32, v3
	v_bfe_i32 v10, v2, 0, 16
	v_add_u32_e32 v2, v3, v10
	v_lshlrev_b32_e32 v3, 1, v154
	v_and_b32_e32 v156, 24, v3
	v_lshrrev_b32_e32 v3, 2, v154
	v_add_u32_e32 v1, 0x2000, v1
	v_and_b32_e32 v157, 4, v3
	v_ashrrev_i32_e32 v3, 31, v1
	v_lshrrev_b32_e32 v3, 22, v3
	v_add_u32_e32 v3, v1, v3
	v_ashrrev_i32_e32 v11, 10, v3
	v_mul_i32_i24_e32 v3, 0x400, v11
	v_sub_u32_e32 v1, v1, v3
	v_lshrrev_b32_e32 v3, 4, v1
	v_bitop3_b32 v1, v3, v1, 32 bitop3:0x6c
	v_ashrrev_i32_e32 v5, 31, v1
	v_lshrrev_b32_e32 v5, 26, v5
	v_add_u32_e32 v5, v1, v5
	s_cselect_b64 s[10:11], -1, 0
	s_ashr_i32 s51, s84, 31
	v_lshlrev_b32_e32 v3, 3, v11
	v_ashrrev_i32_e32 v12, 6, v5
	v_and_b32_e32 v5, 0xc0, v5
	s_lshr_b32 s0, s51, 29
	v_and_b32_e32 v3, -16, v3
	v_sub_u32_e32 v1, v1, v5
	s_add_i32 s0, s84, s0
	v_add_u32_e32 v160, v12, v3
	v_lshlrev_b32_e32 v3, 5, v11
	v_ashrrev_i16_sdwa v1, v4, sext(v1) dst_sel:DWORD dst_unused:UNUSED_PAD src0_sel:DWORD src1_sel:BYTE_0
	s_ashr_i32 s33, s0, 3
	s_and_b32 s0, s0, -8
	v_and_b32_e32 v3, 32, v3
	v_bfe_i32 v13, v1, 0, 16
	s_sub_i32 s47, s84, s0
	s_mov_b64 s[0:1], s[82:83]
	v_add_u32_e32 v1, v3, v13
	v_lshlrev_b32_e32 v3, 1, v160
	s_load_dwordx2 s[6:7], s[0:1], 0xc8
	v_and_b32_e32 v161, 24, v3
	v_lshrrev_b32_e32 v3, 2, v160
	s_ashr_i32 s50, s54, 31
	v_and_b32_e32 v162, 4, v3
	v_lshrrev_b32_e32 v3, 1, v0
	s_cmp_lt_i32 s47, 0
	v_and_b32_e32 v151, 15, v0
	v_and_b32_e32 v150, 24, v3
	v_lshlrev_b32_e32 v0, 2, v0
	s_cselect_b64 s[8:9], -1, 0
	s_lshl_b32 s46, s47, 6
	v_lshlrev_b32_e32 v152, 1, v150
	v_lshlrev_b32_e32 v3, 6, v151
	v_and_b32_e32 v0, 32, v0
	s_cmpk_gt_i32 s84, 0x1ff
	s_mulk_i32 s47, 0x41
	v_readfirstlane_b32 s3, v155
	v_and_b32_e32 v158, 3, v9
	v_and_b32_e32 v163, 3, v12
	v_bitop3_b32 v153, v152, v0, v3 bitop3:0x36
	v_lshlrev_b32_e32 v164, 1, v1
	v_lshlrev_b32_e32 v159, 1, v2
	s_cbranch_scc1 .LBB0_1087
	s_waitcnt lgkmcnt(0)
	s_add_u32 s48, s6, 0x4000000
	s_addc_u32 s49, s7, 0
	s_add_u32 s52, s6, 0xb00000
	s_mov_b32 s0, 0x1fffe0
	s_addc_u32 s53, s7, 0
	s_ashr_i32 s20, s3, 6
	v_and_or_b32 v0, v160, s0, v163
	s_ashr_i32 s22, s3, 8
	s_lshl_b32 s56, s20, 10
	v_or3_b32 v0, v0, v162, v161
	s_waitcnt vmcnt(0)
	v_lshl_add_u32 v128, v0, 11, v164
	v_and_or_b32 v0, v154, s0, v158
	s_and_b64 s[0:1], s[8:9], exec
	s_cselect_b32 s0, s47, s46
	s_add_i32 s0, s0, s33
	s_mul_hi_i32 s1, s0, 0x2aaaaaab
	s_lshr_b32 s2, s1, 31
	s_ashr_i32 s1, s1, 3
	s_add_i32 s1, s1, s2
	s_mul_i32 s12, s1, 12
	s_sub_i32 s2, 0x80, s12
	s_mul_i32 s1, s1, 48
	s_min_u32 s13, s2, 12
	s_sub_i32 s14, s0, s1
	v_or3_b32 v0, v0, v157, v156
	s_sext_i32_i8 s0, s14
	v_cvt_f32_ubyte0_e32 v1, s13
	v_lshl_add_u32 v132, v0, 11, v159
	v_cvt_f32_i32_e32 v0, s0
	v_rcp_iflag_f32_e32 v2, v1
	s_ashr_i32 s0, s0, 30
	s_or_b32 s2, s0, 1
	v_lshl_add_u32 v134, v154, 11, v159
	v_mul_f32_e32 v2, v0, v2
	v_trunc_f32_e32 v2, v2
	v_fma_f32 v0, -v2, v1, v0
	v_cvt_i32_f32_e32 v2, v2
	v_cmp_ge_f32_e64 s[0:1], |v0|, v1
	s_and_b64 s[0:1], s[0:1], exec
	s_cselect_b32 s0, s2, 0
	v_readfirstlane_b32 s1, v2
	s_add_i32 s2, s1, s0
	s_mul_i32 s0, s2, s13
	s_sub_i32 s0, s14, s0
	s_sext_i32_i8 s0, s0
	s_add_i32 s40, s12, s0
	s_ashr_i32 s41, s40, 31
	s_bfe_i64 s[12:13], s[2:3], 0x80000
	s_lshl_b64 s[0:1], s[40:41], 19
	s_lshl_b64 s[12:13], s[12:13], 19
	s_add_u32 s42, s52, s12
	s_addc_u32 s43, s53, s13
	s_add_i32 s41, s56, 0
	s_add_i32 m0, s41, 0x10000
	v_lshl_add_u32 v130, v160, 11, v164
	global_load_lds_dwordx4 v132, s[42:43]
	s_add_i32 m0, s41, 0x12000
	s_add_u32 s12, s42, 0x40000
	global_load_lds_dwordx4 v128, s[42:43]
	s_addc_u32 s13, s43, 0
	s_add_i32 m0, s41, 0x14000
	v_mov_b32_e32 v133, 0
	global_load_lds_dwordx4 v132, s[12:13]
	s_add_i32 m0, s41, 0x16000
	s_add_u32 s0, s48, s0
	s_addc_u32 s1, s49, s1
	s_add_i32 s57, s41, 0x2000
	global_load_lds_dwordx4 v128, s[12:13]
	s_mov_b32 m0, s41
	s_add_u32 s12, s0, 0x40000
	global_load_lds_dwordx4 v134, s[0:1]
	s_mov_b32 m0, s57
	s_addc_u32 s13, s1, 0
	s_add_i32 s58, s41, 0x4000
	global_load_lds_dwordx4 v130, s[0:1]
	s_mov_b32 m0, s58
	s_add_i32 s59, s41, 0x6000
	global_load_lds_dwordx4 v134, s[12:13]
	s_mov_b32 m0, s59
	v_mov_b32_e32 v129, v133
	global_load_lds_dwordx4 v130, s[12:13]
	v_mov_b32_e32 v135, v133
	v_mov_b32_e32 v131, v133
	s_cmp_eq_u32 s22, 1
	v_lshl_add_u64 v[6:7], s[42:43], 0, v[132:133]
	v_lshl_add_u64 v[2:3], s[42:43], 0, v[128:129]
	s_mov_b64 s[12:13], 0x40000
	v_lshl_add_u64 v[0:1], s[0:1], 0, v[134:135]
	s_cselect_b64 s[14:15], -1, 0
	s_cmp_lg_u32 s22, 1
	v_lshl_add_u64 v[4:5], s[0:1], 0, v[130:131]
	s_cbranch_scc1 .LBB0_1070
	s_barrier

; __device__ __forceinline__ unsigned xb_ld(unsigned* p)              { return __hip_atomic_load(p, __ATOMIC_RELAXED, __HIP_MEMORY_SCOPE_AGENT); }
; __device__ __forceinline__ unsigned xb_add(unsigned* p, unsigned v) { return __hip_atomic_fetch_add(p, v, __ATOMIC_RELAXED, __HIP_MEMORY_SCOPE_AGENT); }
; __device__ __forceinline__ void xcd_barrier_complete(unsigned* bar, unsigned x, unsigned& nloc, unsigned& nx) {
;     const unsigned G = gridDim.x * gridDim.y * gridDim.z;
;     unsigned sum, cnt, mine, sp = 0u;
;     for (;;) {
;         sum = 0u; cnt = 0u; mine = 0u;
; #pragma unroll
;         for (unsigned j = 0; j < 16; ++j) { const unsigned c = xb_ld(&bar[XB_XCNT(j)]); sum += c; cnt += (c > 0u) ? 1u : 0u; mine = (j == x) ? c : mine; }
; __device__ __forceinline__ void xcd_barrier(const XcdBarrier& b, const int tid_) {
;     asm volatile("s_waitcnt vmcnt(0)" ::: "memory");
;     __syncthreads();
;     if (tid_ == 0) {
;         unsigned* bar = b.bar;
;         __builtin_amdgcn_s_waitcnt(0);
;         unsigned nloc = b.st[0], nx = b.st[1];
;         if (nloc == 0u) { xcd_barrier_complete(bar, b.x, nloc, nx); b.st[0] = nloc; b.st[1] = nx; }
;         const unsigned old = xb_add(&bar[XB_XSUB(b.x)], 1u);
.LBB0_1107:
	s_setprio 0
	v_readlane_b32 s0, v254, 1
	v_readlane_b32 s1, v254, 2
	s_cmp_gt_i32 s1, 13
	s_cselect_b64 s[0:1], -1, 0
	s_and_b64 s[2:3], s[4:5], s[0:1]
	s_andn2_b64 vcc, exec, s[2:3]
	s_cbranch_vccnz .LBB0_1161
	s_mov_b64 s[4:5], s[82:83]
	v_mbcnt_lo_u32_b32 v0, -1, 0
	v_mbcnt_hi_u32_b32 v0, -1, v0
	s_getreg_b32 s6, hwreg(HW_REG_XCC_ID, 0, 4)
	s_waitcnt vmcnt(0)
	v_sub_u32_e32 v0, 0, v0
	v_cmp_eq_u32_e32 vcc, s52, v0
	s_waitcnt vmcnt(0)
	s_barrier
	s_and_saveexec_b64 s[2:3], vcc
	s_cbranch_execz .LBB0_1160
	s_add_i32 s7, 0, 0x23fc0
	v_mov_b32_e32 v0, s7
	s_load_dwordx2 s[4:5], s[4:5], 0xc8
	s_waitcnt vmcnt(0) expcnt(0) lgkmcnt(0)
	ds_read_b32 v2, v0
	s_add_i32 s7, 0, 0x23fc4
	v_mov_b32_e32 v0, s7
	ds_read_b32 v0, v0
	s_and_b32 s33, s6, 15
	s_waitcnt lgkmcnt(1)
	v_cmp_ne_u32_e32 vcc, 0, v2
	s_cbranch_vccnz .LBB0_1124
	v_readlane_b32 s6, v254, 0
	s_mul_i32 s48, s55, s6
	s_add_u32 s6, s4, 0x1900200
	s_addc_u32 s7, s5, 0
	s_add_u32 s8, s4, 0x1900400
	s_addc_u32 s9, s5, 0
	s_add_u32 s10, s4, 0x1900500
	s_addc_u32 s11, s5, 0
	s_add_u32 s12, s4, 0x1900600
	s_addc_u32 s13, s5, 0
	s_add_u32 s14, s4, 0x1900700
	s_addc_u32 s15, s5, 0
	s_add_u32 s16, s4, 0x1900800
	s_addc_u32 s17, s5, 0
	s_add_u32 s18, s4, 0x1900900
	s_addc_u32 s19, s5, 0
	s_add_u32 s20, s4, 0x1900a00
	s_addc_u32 s21, s5, 0
	s_add_u32 s22, s4, 0x1900b00
	s_addc_u32 s23, s5, 0
	s_add_u32 s24, s4, 0x1900c00
	s_addc_u32 s25, s5, 0
	s_add_u32 s26, s4, 0x1900d00
	s_addc_u32 s27, s5, 0
	s_add_u32 s28, s4, 0x1900e00
	s_addc_u32 s29, s5, 0
	s_add_u32 s30, s4, 0x1900f00
	s_addc_u32 s31, s5, 0
	s_add_u32 s34, s4, 0x1901000
	s_addc_u32 s35, s5, 0
	s_add_u32 s36, s4, 0x1901100
	s_addc_u32 s37, s5, 0
	s_add_u32 s38, s4, 0x1901200
	s_addc_u32 s39, s5, 0
	s_add_u32 s40, s4, 0x1901300
	s_mul_i32 s48, s48, s54
	s_addc_u32 s41, s5, 0
	s_mov_b32 s49, 1
	v_mov_b32_e32 v16, 0
	s_branch .LBB0_1112

; #define PG8_BAR __builtin_amdgcn_s_barrier()
;     __host__ __device__ bool next(int i, Unit& u) const {
;         const long L = (long)i * G + c; if (L >= nwg) return false;
;         int wgid = (int)L; { const int q = nwg / NXCD, r = nwg % NXCD, xcd = wgid % NXCD, off = wgid / NXCD; wgid = (xcd < r ? xcd * (q + 1) : r * (q + 1) + (xcd - r) * q) + off; }
;         const int nig = wgm * nN, gid = wgid / nig, fm = gid * wgm, gsz = (nM - fm) < wgm ? (nM - fm) : wgm;
;         u.pm = fm + ((wgid % nig) % gsz); u.pn = (wgid % nig) / gsz; return true;
; template <class Epi, class Sched, bool ALIGN_EPI = false, bool SP2 = false>
; __device__ __forceinline__ void gemm_phase(PG8_LAS unsigned char* lds, const Gemm g, const Sched& S, const Epi& E, const int tid_in) {
;     const int tid = tid_in, wid = __builtin_amdgcn_readfirstlane(tid >> 6), lane = tid & 63, wr = wid >> 2, wc = wid & 3, fr = lane & 15, fq = lane >> 4;
;     const int K = g.K, nt = K / BK;
;     unsigned voffA[2], voffB[2];
; #pragma unroll
;     for (int i = 0; i < 2; ++i) { int R, C; stage_rc(tid * 16 + i * 8192, R, C); const int Rb = Epi::PERM ? ((R & ~31) + perm32(R & 31)) : R;
;         voffA[i] = (unsigned)(R * K + C) * 2u; voffB[i] = (unsigned)(Rb * K + C) * 2u; }
;     const size_t kstep = (size_t)(BK * 2);
;     const size_t hstep = (size_t)HALF * K * 2;
;     const size_t tstep = 2 * hstep;
;     const unsigned ldsw = (unsigned)wid * 1024u;
;     const int aoff = lds_byte(wr * 64 + fr, fq * 8), boff = lds_byte(wc * 32 + fr, fq * 8);
;     ...
;     Unit cur, nxt; int ui = 0;
;     if (!S.next(0, cur)) return;
;     f32x4 acc[2][2][4][2];
; #pragma unroll
;     for (int a = 0; a < 2; ++a)
; #pragma unroll
;         for (int b = 0; b < 2; ++b)
; #pragma unroll
;             for (int m = 0; m < 4; ++m)
; #pragma unroll
;                 for (int n = 0; n < 2; ++n) acc[a][b][m][n] = (f32x4){0.f, 0.f, 0.f, 0.f};
;     bf16x8 At[4][2], B0[2][2], B1[2][2];
;     const char* cA = (const char*)g.asel(cur.pn) + (size_t)cur.pm * tstep; const char* cB = (const char*)g.Bt + (size_t)cur.pn * tstep;
;     S.a_ready(cur);
;     if constexpr (SP2) {
;         PG8_STAGE(PG8_SB(0, 0), cB, voffB); PG8_STAGE(PG8_SB(0, 1), cB + hstep, voffB); PG8_STAGE(PG8_SA(0, 0), cA, voffA); PG8_STAGE(PG8_SA(0, 1), cA + hstep, voffA);
;         if (wr == 1) PG8_BAR;
.LBB0_1161:
	v_readlane_b32 s2, v254, 1
	v_readlane_b32 s3, v254, 2
	s_cmp_lt_i32 s2, 14
	s_cselect_b64 s[2:3], -1, 0
	s_and_b64 s[4:5], s[2:3], s[0:1]
	s_andn2_b64 vcc, exec, s[4:5]
	s_cbranch_vccnz .LBB0_1182
	v_readlane_b32 s98, v254, 3
	s_cmp_ge_u32 s98, 0x100
	s_cbranch_scc0 .Lmy_prio_13
	s_setprio 1
.Lmy_prio_13:
	v_mbcnt_lo_u32_b32 v8, -1, 0
	v_mbcnt_hi_u32_b32 v8, -1, v8
	s_cmpk_gt_i32 s84, 0x1ff
	v_add_u32_e32 v0, s52, v8
	s_mov_b64 s[0:1], s[82:83]
	v_readfirstlane_b32 s19, v0
	s_cbranch_scc1 .LBB0_1182
	v_lshlrev_b32_e32 v1, 4, v0
	v_add_u32_e32 v2, 0x2000, v1
	v_ashrrev_i32_e32 v3, 31, v2
	v_lshrrev_b32_e32 v3, 22, v3
	v_add_u32_e32 v3, v2, v3
	v_ashrrev_i32_e32 v9, 10, v3
	v_mul_i32_i24_e32 v3, 0x400, v9
	v_sub_u32_e32 v2, v2, v3
	v_lshrrev_b32_e32 v3, 4, v2
	v_bitop3_b32 v2, v3, v2, 32 bitop3:0x6c
	v_ashrrev_i32_e32 v3, 31, v2
	v_lshrrev_b32_e32 v3, 26, v3
	v_add_u32_e32 v3, v2, v3
	v_lshlrev_b32_e32 v4, 3, v9
	v_ashrrev_i32_e32 v10, 6, v3
	v_and_b32_e32 v4, -16, v4
	v_add_u32_e32 v4, v10, v4
	s_load_dwordx2 s[2:3], s[0:1], 0xc8
	v_and_b32_e32 v5, 3, v10
	s_mov_b32 s0, 0x1fffe0
	v_lshrrev_b32_e32 v6, 2, v4
	v_lshlrev_b32_e32 v7, 1, v4
	v_and_b32_e32 v3, 0xc0, v3
	v_and_or_b32 v5, v4, s0, v5
	v_and_b32_e32 v6, 4, v6
	v_and_b32_e32 v7, 24, v7
	v_sub_u32_e32 v2, v2, v3
	v_mov_b32_e32 v3, 1
	v_or3_b32 v5, v5, v6, v7
	v_lshlrev_b32_e32 v6, 5, v9
	v_ashrrev_i16_sdwa v2, v3, sext(v2) dst_sel:DWORD dst_unused:UNUSED_PAD src0_sel:DWORD src1_sel:BYTE_0
	v_and_b32_e32 v6, 32, v6
	v_bfe_i32 v11, v2, 0, 16
	v_add_lshl_u32 v2, v6, v11, 1
	s_waitcnt vmcnt(0)
	v_lshl_add_u32 v128, v5, 11, v2
	v_lshl_add_u32 v130, v4, 11, v2
	v_bfe_i32 v2, v0, 27, 1
	v_lshrrev_b32_e32 v2, 22, v2
	v_add_u32_e32 v2, v1, v2
	v_and_b32_e32 v2, 0xfffffc00, v2
	v_sub_u32_e32 v1, v1, v2
	v_lshrrev_b32_e32 v2, 4, v1
	v_ashrrev_i32_e32 v4, 31, v0
	v_bitop3_b32 v1, v2, v1, 32 bitop3:0x6c
	v_lshrrev_b32_e32 v4, 26, v4
	v_ashrrev_i32_e32 v2, 31, v1
	v_add_u32_e32 v0, v0, v4
	s_waitcnt lgkmcnt(0)
	s_add_u32 s6, s2, 0x16000000
	v_lshrrev_b32_e32 v2, 26, v2
	v_ashrrev_i32_e32 v13, 6, v0
	s_addc_u32 s7, s3, 0
	v_add_u32_e32 v2, v1, v2
	v_lshlrev_b32_e32 v0, 3, v13
	s_add_u32 s33, s2, 0x900000
	v_ashrrev_i32_e32 v12, 6, v2
	v_and_b32_e32 v0, -16, v0
	s_addc_u32 s42, s3, 0
	v_add_u32_e32 v0, v12, v0
	v_and_b32_e32 v4, 3, v12
	s_ashr_i32 s44, s84, 31
	v_and_or_b32 v4, v0, s0, v4
	s_lshr_b32 s0, s44, 29
	s_add_i32 s0, s84, s0
	s_ashr_i32 s1, s0, 3
	s_and_b32 s0, s0, -8
	s_ashr_i32 s16, s19, 6
	s_sub_i32 s0, s84, s0
	s_ashr_i32 s20, s19, 8
	s_lshl_b32 s43, s16, 10
	s_lshl_b32 s9, s0, 6
	s_mul_i32 s8, s0, 0x41
	s_cmp_lt_i32 s0, 0
	s_cselect_b32 s0, s8, s9
	s_add_i32 s0, s0, s1
	s_mul_hi_i32 s1, s0, 0x2aaaaaab
	s_lshr_b32 s8, s1, 31
	s_ashr_i32 s1, s1, 3
	v_lshrrev_b32_e32 v5, 2, v0
	v_lshlrev_b32_e32 v6, 1, v0
	v_and_b32_e32 v2, 0xc0, v2
	s_add_i32 s1, s1, s8
	v_and_b32_e32 v5, 4, v5
	v_and_b32_e32 v6, 24, v6
	v_sub_u32_e32 v1, v1, v2
	s_mul_i32 s8, s1, 12
	v_or3_b32 v4, v4, v5, v6
	v_lshlrev_b32_e32 v5, 5, v13
	v_ashrrev_i16_sdwa v1, v3, sext(v1) dst_sel:DWORD dst_unused:UNUSED_PAD src0_sel:DWORD src1_sel:BYTE_0
	s_sub_i32 s9, 0x80, s8
	v_and_b32_e32 v5, 32, v5
	v_bfe_i32 v14, v1, 0, 16
	s_min_u32 s9, s9, 12
	s_mul_i32 s1, s1, 48
	v_add_lshl_u32 v1, v5, v14, 1
	s_sub_i32 s10, s0, s1
	v_cvt_f32_ubyte0_e32 v3, s9
	v_lshl_add_u32 v132, v4, 11, v1
	v_cvt_f32_i32_e32 v2, s10
	v_rcp_iflag_f32_e32 v4, v3
	v_lshl_add_u32 v134, v0, 11, v1
	s_ashr_i32 s0, s10, 30
	s_or_b32 s11, s0, 1
	v_mul_f32_e32 v0, v2, v4
	v_trunc_f32_e32 v0, v0
	v_fma_f32 v1, -v0, v3, v2
	v_cvt_i32_f32_e32 v0, v0
	v_cmp_ge_f32_e64 s[0:1], |v1|, v3
	s_and_b64 s[0:1], s[0:1], exec
	s_cselect_b32 s0, s11, 0
	v_readfirstlane_b32 s1, v0
	s_add_i32 s18, s1, s0
	s_mul_i32 s0, s18, s9
	s_sub_i32 s0, s10, s0
	s_sext_i32_i8 s0, s0
	s_add_i32 s36, s8, s0
	s_ashr_i32 s37, s36, 31
	s_bfe_i64 s[8:9], s[18:19], 0x80000
	s_lshl_b64 s[0:1], s[36:37], 19
	s_lshl_b64 s[8:9], s[8:9], 19
	s_add_u32 s38, s33, s8
	s_addc_u32 s39, s42, s9
	s_add_i32 s37, s43, 0
	s_add_i32 m0, s37, 0x10000
	v_mov_b32_e32 v133, 0
	global_load_lds_dwordx4 v132, s[38:39]
	s_add_i32 m0, s37, 0x12000
	s_add_u32 s8, s38, 0x40000
	global_load_lds_dwordx4 v128, s[38:39]
	s_addc_u32 s9, s39, 0
	s_add_i32 m0, s37, 0x14000
	v_mov_b32_e32 v129, v133
	global_load_lds_dwordx4 v132, s[8:9]
	s_add_i32 m0, s37, 0x16000
	s_add_u32 s0, s6, s0
	s_addc_u32 s1, s7, s1
	s_add_i32 s45, s37, 0x2000
	global_load_lds_dwordx4 v128, s[8:9]
	s_mov_b32 m0, s37
	s_add_u32 s8, s0, 0x40000
	global_load_lds_dwordx4 v134, s[0:1]
	s_mov_b32 m0, s45
	s_addc_u32 s9, s1, 0
	s_add_i32 s46, s37, 0x4000
	global_load_lds_dwordx4 v130, s[0:1]
	s_mov_b32 m0, s46
	s_add_i32 s47, s37, 0x6000
	global_load_lds_dwordx4 v134, s[8:9]
	s_mov_b32 m0, s47
	v_mov_b32_e32 v135, v133
	global_load_lds_dwordx4 v130, s[8:9]
	v_mov_b32_e32 v131, v133
	s_cmp_eq_u32 s20, 1
	s_mov_b32 s48, 0
	v_lshl_add_u64 v[6:7], s[38:39], 0, v[132:133]
	v_lshl_add_u64 v[2:3], s[38:39], 0, v[128:129]
	s_mov_b64 s[8:9], 0x40000
	v_lshl_add_u64 v[0:1], s[0:1], 0, v[134:135]
	s_cselect_b64 s[10:11], -1, 0
	s_cmp_lg_u32 s20, 1
	v_lshl_add_u64 v[4:5], s[0:1], 0, v[130:131]
	s_cbranch_scc1 .LBB0_1165
	s_barrier

; __device__ __forceinline__ unsigned xb_ld(unsigned* p)              { return __hip_atomic_load(p, __ATOMIC_RELAXED, __HIP_MEMORY_SCOPE_AGENT); }
; __device__ __forceinline__ unsigned xb_add(unsigned* p, unsigned v) { return __hip_atomic_fetch_add(p, v, __ATOMIC_RELAXED, __HIP_MEMORY_SCOPE_AGENT); }
; __device__ __forceinline__ void xcd_barrier_complete(unsigned* bar, unsigned x, unsigned& nloc, unsigned& nx) {
;     const unsigned G = gridDim.x * gridDim.y * gridDim.z;
;     unsigned sum, cnt, mine, sp = 0u;
;     for (;;) {
;         sum = 0u; cnt = 0u; mine = 0u;
; #pragma unroll
;         for (unsigned j = 0; j < 16; ++j) { const unsigned c = xb_ld(&bar[XB_XCNT(j)]); sum += c; cnt += (c > 0u) ? 1u : 0u; mine = (j == x) ? c : mine; }
; __device__ __forceinline__ void xcd_barrier(const XcdBarrier& b, const int tid_) {
;     asm volatile("s_waitcnt vmcnt(0)" ::: "memory");
;     __syncthreads();
;     if (tid_ == 0) {
;         unsigned* bar = b.bar;
;         __builtin_amdgcn_s_waitcnt(0);
;         unsigned nloc = b.st[0], nx = b.st[1];
;         if (nloc == 0u) { xcd_barrier_complete(bar, b.x, nloc, nx); b.st[0] = nloc; b.st[1] = nx; }
;         const unsigned old = xb_add(&bar[XB_XSUB(b.x)], 1u);
.LBB0_1182:
	s_setprio 0
	v_readlane_b32 s0, v254, 1
	v_readlane_b32 s1, v254, 2
	s_cmp_gt_i32 s1, 14
	s_cselect_b64 s[0:1], -1, 0
	s_and_b64 s[2:3], s[4:5], s[0:1]
	s_andn2_b64 vcc, exec, s[2:3]
	s_cbranch_vccnz .LBB0_1236
	s_mov_b64 s[4:5], s[82:83]
	v_mbcnt_lo_u32_b32 v0, -1, 0
	v_mbcnt_hi_u32_b32 v0, -1, v0
	s_getreg_b32 s6, hwreg(HW_REG_XCC_ID, 0, 4)
	s_waitcnt vmcnt(0)
	v_sub_u32_e32 v0, 0, v0
	v_cmp_eq_u32_e32 vcc, s52, v0
	s_waitcnt vmcnt(0)
	s_barrier
	s_and_saveexec_b64 s[2:3], vcc
	s_cbranch_execz .LBB0_1235
	s_add_i32 s7, 0, 0x23fc0
	v_mov_b32_e32 v0, s7
	s_load_dwordx2 s[4:5], s[4:5], 0xc8
	s_waitcnt vmcnt(0) expcnt(0) lgkmcnt(0)
	ds_read_b32 v2, v0
	s_add_i32 s7, 0, 0x23fc4
	v_mov_b32_e32 v0, s7
	ds_read_b32 v0, v0
	s_and_b32 s33, s6, 15
	s_waitcnt lgkmcnt(1)
	v_cmp_ne_u32_e32 vcc, 0, v2
	s_cbranch_vccnz .LBB0_1199
	v_readlane_b32 s6, v254, 0
	s_mul_i32 s48, s55, s6
	s_add_u32 s6, s4, 0x1900200
	s_addc_u32 s7, s5, 0
	s_add_u32 s8, s4, 0x1900400
	s_addc_u32 s9, s5, 0
	s_add_u32 s10, s4, 0x1900500
	s_addc_u32 s11, s5, 0
	s_add_u32 s12, s4, 0x1900600
	s_addc_u32 s13, s5, 0
	s_add_u32 s14, s4, 0x1900700
	s_addc_u32 s15, s5, 0
	s_add_u32 s16, s4, 0x1900800
	s_addc_u32 s17, s5, 0
	s_add_u32 s18, s4, 0x1900900
	s_addc_u32 s19, s5, 0
	s_add_u32 s20, s4, 0x1900a00
	s_addc_u32 s21, s5, 0
	s_add_u32 s22, s4, 0x1900b00
	s_addc_u32 s23, s5, 0
	s_add_u32 s24, s4, 0x1900c00
	s_addc_u32 s25, s5, 0
	s_add_u32 s26, s4, 0x1900d00
	s_addc_u32 s27, s5, 0
	s_add_u32 s28, s4, 0x1900e00
	s_addc_u32 s29, s5, 0
	s_add_u32 s30, s4, 0x1900f00
	s_addc_u32 s31, s5, 0
	s_add_u32 s34, s4, 0x1901000
	s_addc_u32 s35, s5, 0
	s_add_u32 s36, s4, 0x1901100
	s_addc_u32 s37, s5, 0
	s_add_u32 s38, s4, 0x1901200
	s_addc_u32 s39, s5, 0
	s_add_u32 s40, s4, 0x1901300
	s_mul_i32 s48, s48, s54
	s_addc_u32 s41, s5, 0
	s_mov_b32 s49, 1
	v_mov_b32_e32 v16, 0
	s_branch .LBB0_1187
